# non-temporal hint on the last-use residual-stream (Y) loads: P12 row loads and the P8/P11 epilogue residual loads
# baseline (speedup 1.0000x reference)
; __device__ __forceinline__ f32x2 ln_stats(f32x2 sm) { const float mu = sm[0] * (1.f / D); const float var = fmaxf(sm[1] * (1.f / D) - mu * mu, 0.f); return (f32x2){mu, 1.0f / sqrtf(var + LN_EPS)}; }
;     __device__ __forceinline__ void operator()(const f32x4 (&acc)[2][2][4][2], const Unit& u, int wr, int wc, int fr, int fq) const {
;         const int row0 = u.pm * BM + wr * 64 + fr, col0 = u.pn * BM + wc * 32 + 4 * fq;
;         f32x4 gg[2][2], bb[2][2];
; #pragma unroll
;         for (int bj = 0; bj < 2; ++bj)
; #pragma unroll
;             for (int n = 0; n < 2; ++n) { gg[bj][n] = (f32x4){1.f, 1.f, 1.f, 1.f}; bb[bj][n] = (f32x4){0.f, 0.f, 0.f, 0.f};
;                 if (rin) { gg[bj][n] = *(const f32x4*)(lg + col0 + bj * HALF + n * 16); bb[bj][n] = *(const f32x4*)(lb + col0 + bj * HALF + n * 16); } }
; #pragma unroll
;         for (int ai = 0; ai < 2; ++ai)
; #pragma unroll
;             for (int m2 = 0; m2 < 2; ++m2) {
;                 f32x4 xv[2][2][2]; f32x2 st[2];
; #pragma unroll
;                 for (int mm = 0; mm < 2; ++mm) {
;                     const int r = row0 + ai * HALF + (2 * m2 + mm) * 16;
;                     st[mm] = (f32x2){0.f, 1.f};
;                     if (rin) st[mm] = ln_stats(*(const f32x2*)(rin + 2 * (size_t)r));
; #pragma unroll
;                     for (int bj = 0; bj < 2; ++bj)
; #pragma unroll
;                         for (int n = 0; n < 2; ++n) { const f32x4* rp = (const f32x4*)(res + (size_t)r * D + col0 + bj * HALF + n * 16); xv[mm][bj][n] = stream ? __builtin_nontemporal_load(rp) : *rp; }
.LBB0_948:
	v_lshl_add_u32 v194, s0, 8, v177
	v_ashrrev_i32_e32 v195, 31, v194
	v_lshlrev_b64 v[200:201], 3, v[194:195]
	v_lshl_add_u64 v[54:55], s[54:55], 0, v[200:201]
	global_load_dwordx2 v[230:231], v[54:55], off
	v_lshl_or_b32 v190, s60, 8, v208
	v_ashrrev_i32_e32 v191, 31, v190
	v_readlane_b32 s76, v254, 11
	v_lshlrev_b64 v[52:53], 2, v[190:191]
	v_readlane_b32 s78, v254, 13
	v_readlane_b32 s79, v254, 14
	v_lshl_add_u64 v[192:193], s[38:39], 0, v[52:53]
	v_lshlrev_b64 v[54:55], 13, v[194:195]
	v_readlane_b32 s80, v254, 15
	v_readlane_b32 s81, v254, 16
	s_mov_b64 s[42:43], s[78:79]
	v_lshl_add_u64 v[232:233], v[192:193], 0, v[54:55]
	s_mov_b64 s[44:45], s[80:81]
	v_lshl_add_u64 v[54:55], s[42:43], 0, v[52:53]
	global_load_dwordx4 v[214:217], v[232:233], off
	global_load_dwordx4 v[218:221], v[232:233], off offset:64
	global_load_dwordx4 v[92:95], v[54:55], off
	global_load_dwordx4 v[76:79], v[54:55], off offset:64
	v_lshl_add_u64 v[52:53], s[44:45], 0, v[52:53]
	global_load_dwordx4 v[88:91], v[52:53], off
	global_load_dwordx4 v[72:75], v[52:53], off offset:64
	v_lshlrev_b64 v[56:57], 11, v[194:195]
	v_or_b32_e32 v204, 16, v194
	v_lshl_add_u64 v[206:207], v[56:57], 0, v[190:191]
	global_load_dwordx4 v[68:71], v[54:55], off offset:512
	global_load_dwordx4 v[56:59], v[54:55], off offset:576
	global_load_dwordx4 v[64:67], v[52:53], off offset:512 nt
	s_nop 0
	global_load_dwordx4 v[52:55], v[52:53], off offset:576 nt
	v_ashrrev_i32_e32 v205, 31, v204
	v_lshlrev_b64 v[196:197], 3, v[204:205]
	v_lshlrev_b64 v[160:161], 13, v[204:205]
	v_lshl_add_u64 v[162:163], s[54:55], 0, v[196:197]
	v_lshl_add_u64 v[202:203], v[192:193], 0, v[160:161]
	global_load_dwordx4 v[222:225], v[232:233], off offset:512 nt
	global_load_dwordx4 v[226:229], v[232:233], off offset:576 nt
	global_load_dwordx2 v[198:199], v[162:163], off
	global_load_dwordx4 v[172:175], v[202:203], off nt
	global_load_dwordx4 v[168:171], v[202:203], off offset:64 nt
	global_load_dwordx4 v[164:167], v[202:203], off offset:512 nt
	s_nop 0
	global_load_dwordx4 v[160:163], v[202:203], off offset:576 nt
	v_or_b32_e32 v240, 16, v206
	v_mov_b32_e32 v241, v207
	v_lshl_add_u64 v[238:239], v[206:207], 1, s[6:7]
	v_lshl_add_u64 v[242:243], v[240:241], 2, s[38:39]
	v_lshl_add_u64 v[240:241], v[240:241], 1, s[6:7]
	v_readlane_b32 s77, v254, 12
	v_readlane_b32 s82, v254, 17
	v_readlane_b32 s83, v254, 18
	v_readlane_b32 s84, v254, 19
	v_readlane_b32 s85, v254, 20
	v_readlane_b32 s86, v254, 21
	v_readlane_b32 s87, v254, 22
	v_readlane_b32 s88, v254, 23
	v_readlane_b32 s89, v254, 24
	v_readlane_b32 s90, v254, 25
	v_readlane_b32 s91, v254, 26
	s_waitcnt vmcnt(0)
; __device__ __forceinline__ unsigned cvt_pk_bf16(float lo, float hi) { unsigned r; asm volatile("v_cvt_pk_bf16_f32 %0, %1, %2" : "=v"(r) : "v"(lo), "v"(hi)); return r; }
;     __device__ __forceinline__ void operator()(const f32x4 (&acc)[2][2][4][2], const Unit& u, int wr, int wc, int fr, int fq) const {
;     ...
;                 for (int mm = 0; mm < 2; ++mm) {
;                     const int r = row0 + ai * HALF + (2 * m2 + mm) * 16;
;                     float ps = 0.f, pq = 0.f;
; #pragma unroll
;                     for (int bj = 0; bj < 2; ++bj)
; #pragma unroll
;                         for (int n = 0; n < 2; ++n) {
;                             const f32x4 x = (xv[mm][bj][n] - st[mm][0]) * (gg[bj][n] * st[mm][1]) + bb[bj][n];
;                             const f32x4 o = x * alpha + acc[ai][bj][2 * m2 + mm][n] * scale;
;                             const size_t off = (size_t)r * D + col0 + bj * HALF + n * 16;
;                             *(f32x4*)(Y + off) = o;
;                             if (yb) { u32x2 w; w.x = cvt_pk_bf16(o[0], o[1]); w.y = cvt_pk_bf16(o[2], o[3]); *(u32x2*)(yb + off) = w; }
;                             ps += (o[0] + o[1]) + (o[2] + o[3]); pq += (o[0] * o[0] + o[1] * o[1]) + (o[2] * o[2] + o[3] * o[3]);
;                         }
;                     if (rout) {
;                         ps += __shfl_xor(ps, 16); pq += __shfl_xor(pq, 16); ps += __shfl_xor(ps, 32); pq += __shfl_xor(pq, 32);
;                         if (fq == 0) { atomicAdd(rout + 2 * (size_t)r, ps); atomicAdd(rout + 2 * (size_t)r + 1, pq); }
	v_pk_mul_f32 v[230:231], v[230:231], s[18:19] op_sel_hi:[1,0]
	s_nop 0
	v_fma_f32 v195, -v230, v230, v231
	v_max_f32_e32 v195, 0, v195
	v_add_f32_e32 v195, 0x3727c5ac, v195
	v_mul_f32_e32 v231, 0x4f800000, v195
	v_cmp_gt_f32_e32 vcc, s52, v195
	v_sub_f32_e32 v217, v217, v230
	s_nop 0
	v_cndmask_b32_e32 v195, v195, v231, vcc
	v_sqrt_f32_e32 v231, v195
	v_sub_f32_e32 v216, v216, v230
	v_sub_f32_e32 v215, v215, v230
	v_sub_f32_e32 v214, v214, v230
	v_add_u32_e32 v237, -1, v231
	v_add_u32_e32 v244, 1, v231
	v_fma_f32 v245, -v237, v231, v195
	v_fma_f32 v246, -v244, v231, v195
	v_cmp_ge_f32_e64 s[0:1], 0, v245
	v_sub_f32_e32 v221, v221, v230
	v_sub_f32_e32 v220, v220, v230
	v_cndmask_b32_e64 v231, v231, v237, s[0:1]
	v_cmp_lt_f32_e64 s[0:1], 0, v246
	v_sub_f32_e32 v219, v219, v230
	v_sub_f32_e32 v218, v218, v230
	v_cndmask_b32_e64 v231, v231, v244, s[0:1]
	v_mul_f32_e32 v237, 0x37800000, v231
	v_cndmask_b32_e32 v231, v231, v237, vcc
	v_cmp_class_f32_e32 vcc, v195, v212
	s_nop 1
	v_cndmask_b32_e32 v195, v231, v195, vcc
	v_div_scale_f32 v231, s[0:1], v195, v195, 1.0
	v_rcp_f32_e32 v237, v231
	v_div_scale_f32 v244, vcc, 1.0, v195, 1.0
	v_fma_f32 v245, -v231, v237, 1.0
	v_fmac_f32_e32 v237, v245, v237
	v_mul_f32_e32 v245, v244, v237
	v_fma_f32 v246, -v231, v245, v244
	v_fmac_f32_e32 v245, v246, v237
	v_fma_f32 v231, -v231, v245, v244
	v_div_fmas_f32 v231, v231, v237, v245
	v_div_fixup_f32 v244, v231, v195, 1.0
	v_pk_mul_f32 v[246:247], v[94:95], v[244:245] op_sel_hi:[1,0]
	v_pk_mul_f32 v[248:249], v[92:93], v[244:245] op_sel_hi:[1,0]
	v_pk_mul_f32 v[250:251], v[78:79], v[244:245] op_sel_hi:[1,0]
	v_pk_mul_f32 v[252:253], v[76:77], v[244:245] op_sel_hi:[1,0]
	v_pk_fma_f32 v[214:215], v[214:215], v[248:249], v[88:89]
	v_pk_fma_f32 v[216:217], v[216:217], v[246:247], v[90:91]
	v_pk_fma_f32 v[218:219], v[218:219], v[252:253], v[72:73]
	v_pk_fma_f32 v[220:221], v[220:221], v[250:251], v[74:75]
	v_pk_fma_f32 v[158:159], v[216:217], s[20:21], v[158:159] op_sel_hi:[1,0,1]
	v_pk_fma_f32 v[156:157], v[214:215], s[20:21], v[156:157] op_sel_hi:[1,0,1]
	v_pk_fma_f32 v[154:155], v[220:221], s[20:21], v[154:155] op_sel_hi:[1,0,1]
	v_pk_fma_f32 v[152:153], v[218:219], s[20:21], v[152:153] op_sel_hi:[1,0,1]
	v_add_f32_e32 v195, v156, v157
	v_add_f32_e32 v216, v159, v158
	global_store_dwordx4 v[232:233], v[156:159], off
	v_cvt_pk_bf16_f32 v214, v156, v157
	v_cvt_pk_bf16_f32 v215, v158, v159
	v_mul_f32_e32 v217, v157, v157
	v_add_f32_e32 v218, v152, v153
	v_mul_f32_e32 v158, v158, v158
	v_add_f32_e32 v219, v155, v154
	v_mul_f32_e32 v220, v153, v153
	v_mul_f32_e32 v221, v154, v154
	v_add_f32_e32 v195, v195, v216
	global_store_dwordx2 v[238:239], v[214:215], off
	v_fmac_f32_e32 v217, v156, v156
	v_fmac_f32_e32 v158, v159, v159
	global_store_dwordx4 v[242:243], v[152:155], off
	v_cvt_pk_bf16_f32 v156, v152, v153
	v_fmac_f32_e32 v220, v152, v152
	v_fmac_f32_e32 v221, v155, v155
	v_add_f32_e32 v153, v218, v219
	v_add_f32_e32 v152, 0, v195
	v_cvt_pk_bf16_f32 v157, v154, v155
	v_add_f32_e32 v154, v217, v158
	v_add_f32_e32 v195, v153, v152
	v_add_f32_e32 v152, v220, v221
	global_store_dwordx2 v[240:241], v[156:157], off
	v_add_f32_e32 v216, v154, v152
	v_sub_f32_e32 v155, v225, v230
	v_sub_f32_e32 v154, v224, v230
	v_sub_f32_e32 v157, v223, v230
	v_sub_f32_e32 v156, v222, v230
	v_pk_mul_f32 v[158:159], v[70:71], v[244:245] op_sel_hi:[1,0]
	v_pk_mul_f32 v[214:215], v[68:69], v[244:245] op_sel_hi:[1,0]
	v_or_b32_e32 v152, 0x80, v206
	v_mov_b32_e32 v153, v207
	v_pk_fma_f32 v[156:157], v[156:157], v[214:215], v[64:65]
	v_pk_fma_f32 v[154:155], v[154:155], v[158:159], v[66:67]
	v_pk_fma_f32 v[148:149], v[156:157], s[20:21], v[148:149] op_sel_hi:[1,0,1]
	v_pk_fma_f32 v[150:151], v[154:155], s[20:21], v[150:151] op_sel_hi:[1,0,1]
	v_lshl_add_u64 v[154:155], v[152:153], 2, s[38:39]
	v_lshl_add_u64 v[152:153], v[152:153], 1, s[6:7]
	global_store_dwordx4 v[154:155], v[148:151], off
	v_cvt_pk_bf16_f32 v154, v148, v149
	v_cvt_pk_bf16_f32 v155, v150, v151
	global_store_dwordx2 v[152:153], v[154:155], off
	v_add_f32_e32 v152, v148, v149
	v_mul_f32_e32 v149, v149, v149
	v_fmac_f32_e32 v149, v148, v148
	v_mul_f32_e32 v148, v150, v150
	v_add_f32_e32 v153, v151, v150
	v_fmac_f32_e32 v148, v151, v151
	v_add_f32_e32 v152, v152, v153
	v_add_f32_e32 v148, v149, v148
	v_add_f32_e32 v156, v152, v195
	v_add_f32_e32 v157, v148, v216
	v_sub_f32_e32 v149, v229, v230
	v_sub_f32_e32 v148, v228, v230
	v_sub_f32_e32 v151, v227, v230
	v_sub_f32_e32 v150, v226, v230
	v_pk_mul_f32 v[152:153], v[58:59], v[244:245] op_sel_hi:[1,0]
	v_pk_mul_f32 v[154:155], v[56:57], v[244:245] op_sel_hi:[1,0]
	v_pk_fma_f32 v[148:149], v[148:149], v[152:153], v[54:55]
	v_pk_fma_f32 v[154:155], v[150:151], v[154:155], v[52:53]
	v_pk_fma_f32 v[150:151], v[148:149], s[20:21], v[146:147] op_sel_hi:[1,0,1]
	v_pk_fma_f32 v[148:149], v[154:155], s[20:21], v[144:145] op_sel_hi:[1,0,1]
	v_mul_f32_e32 v145, v150, v150
	v_mul_f32_e32 v144, v149, v149
	v_fmac_f32_e32 v144, v148, v148
	v_fmac_f32_e32 v145, v151, v151
	v_add_f32_e32 v144, v144, v145
	v_add_f32_e32 v146, v144, v157
	v_add_f32_e32 v144, v148, v149
	v_add_f32_e32 v145, v151, v150
	v_add_f32_e32 v144, v144, v145
	v_and_b32_e32 v145, 64, v213
	v_add_f32_e32 v147, v144, v156
	v_xor_b32_e32 v144, 16, v213
	v_add_u32_e32 v152, 64, v145
	v_cmp_lt_i32_e32 vcc, v144, v152
	v_or_b32_e32 v206, 0x90, v206
	s_nop 0
	v_cndmask_b32_e32 v144, v213, v144, vcc
	v_lshlrev_b32_e32 v156, 2, v144
	ds_bpermute_b32 v154, v156, v146
	ds_bpermute_b32 v153, v156, v147
	v_lshl_add_u64 v[144:145], v[206:207], 2, s[38:39]
	global_store_dwordx4 v[144:145], v[148:151], off
	s_waitcnt lgkmcnt(1)
	v_add_f32_e32 v145, v146, v154
	v_xor_b32_e32 v146, 32, v213
	v_cmp_lt_i32_e32 vcc, v146, v152
	s_waitcnt lgkmcnt(0)
	v_add_f32_e32 v144, v147, v153
	v_cvt_pk_bf16_f32 v148, v148, v149
	v_cvt_pk_bf16_f32 v149, v150, v151
	v_lshl_add_u64 v[150:151], v[206:207], 1, s[6:7]
	v_cndmask_b32_e32 v146, v213, v146, vcc
	v_lshlrev_b32_e32 v157, 2, v146
	ds_bpermute_b32 v146, v157, v144
	ds_bpermute_b32 v147, v157, v145
	global_store_dwordx2 v[150:151], v[148:149], off
	s_and_saveexec_b64 s[0:1], s[4:5]
	s_cbranch_execz .LBB0_950
	v_lshl_add_u64 v[148:149], s[8:9], 0, v[200:201]
	s_waitcnt lgkmcnt(1)
	v_add_f32_e32 v144, v144, v146
	s_waitcnt lgkmcnt(0)
	v_add_f32_e32 v145, v145, v147
	global_atomic_add_f32 v[148:149], v144, off
	global_atomic_add_f32 v[148:149], v145, off offset:4

; __device__ __forceinline__ f32x2 ln_stats(f32x2 sm) { const float mu = sm[0] * (1.f / D); const float var = fmaxf(sm[1] * (1.f / D) - mu * mu, 0.f); return (f32x2){mu, 1.0f / sqrtf(var + LN_EPS)}; }
;     __device__ __forceinline__ void operator()(const f32x4 (&acc)[2][2][4][2], const Unit& u, int wr, int wc, int fr, int fq) const {
;     ...
;                 f32x4 xv[2][2][2]; f32x2 st[2];
; #pragma unroll
;                 for (int mm = 0; mm < 2; ++mm) {
;                     const int r = row0 + ai * HALF + (2 * m2 + mm) * 16;
;                     st[mm] = (f32x2){0.f, 1.f};
;                     if (rin) st[mm] = ln_stats(*(const f32x2*)(rin + 2 * (size_t)r));
; #pragma unroll
;                     for (int bj = 0; bj < 2; ++bj)
; #pragma unroll
;                         for (int n = 0; n < 2; ++n) { const f32x4* rp = (const f32x4*)(res + (size_t)r * D + col0 + bj * HALF + n * 16); xv[mm][bj][n] = stream ? __builtin_nontemporal_load(rp) : *rp; }
.LBB0_952:
	s_or_b64 exec, exec, s[0:1]
	v_or_b32_e32 v128, 32, v194
	v_ashrrev_i32_e32 v129, 31, v128
	v_lshlrev_b64 v[152:153], 3, v[128:129]
	s_waitcnt lgkmcnt(0)
	v_lshl_add_u64 v[130:131], s[54:55], 0, v[152:153]
	global_load_dwordx2 v[174:175], v[130:131], off
	v_lshlrev_b64 v[130:131], 13, v[128:129]
	v_lshl_add_u64 v[196:197], v[192:193], 0, v[130:131]
	global_load_dwordx4 v[158:161], v[196:197], off nt
	global_load_dwordx4 v[162:165], v[196:197], off offset:64 nt
	global_load_dwordx4 v[166:169], v[196:197], off offset:512 nt
	v_or_b32_e32 v150, 48, v194
	v_ashrrev_i32_e32 v151, 31, v150
	v_lshlrev_b64 v[144:145], 3, v[150:151]
	v_lshlrev_b64 v[130:131], 13, v[150:151]
	v_lshlrev_b64 v[128:129], 11, v[128:129]
	v_lshl_add_u64 v[132:133], s[54:55], 0, v[144:145]
	v_lshl_add_u64 v[148:149], v[192:193], 0, v[130:131]
	v_lshl_add_u64 v[154:155], v[128:129], 0, v[190:191]
	global_load_dwordx4 v[170:173], v[196:197], off offset:576 nt
	global_load_dwordx2 v[146:147], v[132:133], off
	global_load_dwordx4 v[140:143], v[148:149], off nt
	global_load_dwordx4 v[136:139], v[148:149], off offset:64 nt
	s_nop 0
	global_load_dwordx4 v[132:135], v[148:149], off offset:512 nt
	global_load_dwordx4 v[128:131], v[148:149], off offset:576 nt
	v_lshl_add_u64 v[198:199], v[154:155], 1, s[6:7]
	v_or_b32_e32 v200, 16, v154
	v_mov_b32_e32 v201, v155
	v_lshl_add_u64 v[204:205], v[200:201], 2, s[38:39]
	v_or_b32_e32 v202, 0x80, v154
	v_mov_b32_e32 v203, v155
	v_lshl_add_u64 v[200:201], v[200:201], 1, s[6:7]
	v_or_b32_e32 v154, 0x90, v154
	s_waitcnt vmcnt(9)
	v_pk_mul_f32 v[174:175], v[174:175], s[18:19] op_sel_hi:[1,0]
	s_nop 0
	v_fma_f32 v175, -v174, v174, v175
	v_max_f32_e32 v175, 0, v175
	v_add_f32_e32 v175, 0x3727c5ac, v175
	v_mul_f32_e32 v195, 0x4f800000, v175
	v_cmp_gt_f32_e32 vcc, s52, v175
	s_waitcnt vmcnt(8)
	v_sub_f32_e32 v161, v161, v174
	v_sub_f32_e32 v160, v160, v174
	v_cndmask_b32_e32 v175, v175, v195, vcc
	v_sqrt_f32_e32 v195, v175
	v_sub_f32_e32 v159, v159, v174
	v_sub_f32_e32 v158, v158, v174
	s_waitcnt vmcnt(7)
	v_sub_f32_e32 v165, v165, v174
	v_add_u32_e32 v206, -1, v195
	v_add_u32_e32 v207, 1, v195
	v_fma_f32 v214, -v206, v195, v175
	v_fma_f32 v215, -v207, v195, v175
	v_cmp_ge_f32_e64 s[0:1], 0, v214
	v_sub_f32_e32 v164, v164, v174
	v_sub_f32_e32 v163, v163, v174
	v_cndmask_b32_e64 v195, v195, v206, s[0:1]
	v_cmp_lt_f32_e64 s[0:1], 0, v215
	v_sub_f32_e32 v162, v162, v174
	s_waitcnt vmcnt(6)
; __device__ __forceinline__ unsigned cvt_pk_bf16(float lo, float hi) { unsigned r; asm volatile("v_cvt_pk_bf16_f32 %0, %1, %2" : "=v"(r) : "v"(lo), "v"(hi)); return r; }
;     __device__ __forceinline__ void operator()(const f32x4 (&acc)[2][2][4][2], const Unit& u, int wr, int wc, int fr, int fq) const {
;     ...
;                 for (int mm = 0; mm < 2; ++mm) {
;                     const int r = row0 + ai * HALF + (2 * m2 + mm) * 16;
;                     float ps = 0.f, pq = 0.f;
; #pragma unroll
;                     for (int bj = 0; bj < 2; ++bj)
; #pragma unroll
;                         for (int n = 0; n < 2; ++n) {
;                             const f32x4 x = (xv[mm][bj][n] - st[mm][0]) * (gg[bj][n] * st[mm][1]) + bb[bj][n];
;                             const f32x4 o = x * alpha + acc[ai][bj][2 * m2 + mm][n] * scale;
;                             const size_t off = (size_t)r * D + col0 + bj * HALF + n * 16;
;                             *(f32x4*)(Y + off) = o;
;                             if (yb) { u32x2 w; w.x = cvt_pk_bf16(o[0], o[1]); w.y = cvt_pk_bf16(o[2], o[3]); *(u32x2*)(yb + off) = w; }
;                             ps += (o[0] + o[1]) + (o[2] + o[3]); pq += (o[0] * o[0] + o[1] * o[1]) + (o[2] * o[2] + o[3] * o[3]);
;                         }
;                     if (rout) {
;                         ps += __shfl_xor(ps, 16); pq += __shfl_xor(pq, 16); ps += __shfl_xor(ps, 32); pq += __shfl_xor(pq, 32);
;                         if (fq == 0) { atomicAdd(rout + 2 * (size_t)r, ps); atomicAdd(rout + 2 * (size_t)r + 1, pq); }
	v_sub_f32_e32 v169, v169, v174
	v_cndmask_b32_e64 v195, v195, v207, s[0:1]
	v_mul_f32_e32 v206, 0x37800000, v195
	v_cndmask_b32_e32 v195, v195, v206, vcc
	v_cmp_class_f32_e32 vcc, v175, v212
	v_sub_f32_e32 v168, v168, v174
	v_sub_f32_e32 v167, v167, v174
	v_cndmask_b32_e32 v175, v195, v175, vcc
	v_div_scale_f32 v195, s[0:1], v175, v175, 1.0
	v_rcp_f32_e32 v206, v195
	v_div_scale_f32 v207, vcc, 1.0, v175, 1.0
	v_sub_f32_e32 v166, v166, v174
	v_fma_f32 v214, -v195, v206, 1.0
	v_fmac_f32_e32 v206, v214, v206
	v_mul_f32_e32 v214, v207, v206
	v_fma_f32 v215, -v195, v214, v207
	v_fmac_f32_e32 v214, v215, v206
	v_fma_f32 v195, -v195, v214, v207
	v_div_fmas_f32 v195, v195, v206, v214
	v_div_fixup_f32 v206, v195, v175, 1.0
	v_pk_mul_f32 v[214:215], v[94:95], v[206:207] op_sel_hi:[1,0]
	v_pk_mul_f32 v[216:217], v[92:93], v[206:207] op_sel_hi:[1,0]
	v_pk_mul_f32 v[218:219], v[78:79], v[206:207] op_sel_hi:[1,0]
	v_pk_mul_f32 v[220:221], v[76:77], v[206:207] op_sel_hi:[1,0]
	v_pk_fma_f32 v[158:159], v[158:159], v[216:217], v[88:89]
	v_pk_fma_f32 v[160:161], v[160:161], v[214:215], v[90:91]
	v_pk_mul_f32 v[222:223], v[70:71], v[206:207] op_sel_hi:[1,0]
	v_pk_fma_f32 v[162:163], v[162:163], v[220:221], v[72:73]
	v_pk_fma_f32 v[164:165], v[164:165], v[218:219], v[74:75]
	v_pk_fma_f32 v[126:127], v[160:161], s[20:21], v[126:127] op_sel_hi:[1,0,1]
	v_pk_fma_f32 v[124:125], v[158:159], s[20:21], v[124:125] op_sel_hi:[1,0,1]
	v_pk_fma_f32 v[168:169], v[168:169], v[222:223], v[66:67]
	v_pk_fma_f32 v[122:123], v[164:165], s[20:21], v[122:123] op_sel_hi:[1,0,1]
	v_pk_fma_f32 v[120:121], v[162:163], s[20:21], v[120:121] op_sel_hi:[1,0,1]
	global_store_dwordx4 v[196:197], v[124:127], off
	v_cvt_pk_bf16_f32 v158, v124, v125
	v_add_f32_e32 v160, v124, v125
	v_add_f32_e32 v161, v127, v126
	v_pk_mul_f32 v[224:225], v[68:69], v[206:207] op_sel_hi:[1,0]
	v_pk_fma_f32 v[118:119], v[168:169], s[20:21], v[118:119] op_sel_hi:[1,0,1]
	v_cvt_pk_bf16_f32 v159, v126, v127
	v_mul_f32_e32 v162, v125, v125
	v_mul_f32_e32 v126, v126, v126
	v_add_f32_e32 v163, v120, v121
	v_add_f32_e32 v164, v123, v122
	v_mul_f32_e32 v165, v121, v121
	v_mul_f32_e32 v168, v122, v122
	global_store_dwordx2 v[198:199], v[158:159], off
	v_add_f32_e32 v158, v160, v161
	v_pk_fma_f32 v[166:167], v[166:167], v[224:225], v[64:65]
	v_fmac_f32_e32 v162, v124, v124
	v_fmac_f32_e32 v126, v127, v127
	global_store_dwordx4 v[204:205], v[120:123], off
	v_cvt_pk_bf16_f32 v124, v120, v121
	v_fmac_f32_e32 v165, v120, v120
	v_fmac_f32_e32 v168, v123, v123
	v_add_f32_e32 v121, v163, v164
	v_add_f32_e32 v120, 0, v158
	v_cvt_pk_bf16_f32 v125, v122, v123
	v_add_f32_e32 v122, v162, v126
	global_store_dwordx2 v[200:201], v[124:125], off
	v_add_f32_e32 v123, v165, v168
	v_add_f32_e32 v124, v121, v120
	v_pk_fma_f32 v[116:117], v[166:167], s[20:21], v[116:117] op_sel_hi:[1,0,1]
	v_lshl_add_u64 v[120:121], v[202:203], 2, s[38:39]
	v_add_f32_e32 v125, v122, v123
	global_store_dwordx4 v[120:121], v[116:119], off
	v_cvt_pk_bf16_f32 v120, v116, v117
	v_lshl_add_u64 v[122:123], v[202:203], 1, s[6:7]
	v_cvt_pk_bf16_f32 v121, v118, v119
	global_store_dwordx2 v[122:123], v[120:121], off
	v_add_f32_e32 v120, v116, v117
	v_mul_f32_e32 v117, v117, v117
	v_fmac_f32_e32 v117, v116, v116
	v_mul_f32_e32 v116, v118, v118
	v_add_f32_e32 v121, v119, v118
	v_fmac_f32_e32 v116, v119, v119
	v_add_f32_e32 v120, v120, v121
	v_add_f32_e32 v116, v117, v116
	v_add_f32_e32 v124, v120, v124
	v_add_f32_e32 v125, v116, v125
	s_waitcnt vmcnt(11)
	v_sub_f32_e32 v117, v173, v174
	v_sub_f32_e32 v116, v172, v174
	v_sub_f32_e32 v119, v171, v174
	v_sub_f32_e32 v118, v170, v174
	v_pk_mul_f32 v[120:121], v[58:59], v[206:207] op_sel_hi:[1,0]
	v_pk_mul_f32 v[122:123], v[56:57], v[206:207] op_sel_hi:[1,0]
	v_pk_fma_f32 v[116:117], v[116:117], v[120:121], v[54:55]
	v_pk_fma_f32 v[122:123], v[118:119], v[122:123], v[52:53]
	v_pk_fma_f32 v[118:119], v[116:117], s[20:21], v[114:115] op_sel_hi:[1,0,1]
	v_pk_fma_f32 v[116:117], v[122:123], s[20:21], v[112:113] op_sel_hi:[1,0,1]
	v_mul_f32_e32 v113, v118, v118
	v_mul_f32_e32 v112, v117, v117
	v_fmac_f32_e32 v112, v116, v116
	v_fmac_f32_e32 v113, v119, v119
	v_add_f32_e32 v112, v112, v113
	v_add_f32_e32 v114, v112, v125
	v_add_f32_e32 v112, v116, v117
	v_add_f32_e32 v113, v119, v118
	v_add_f32_e32 v112, v112, v113
	v_add_f32_e32 v115, v112, v124
	ds_bpermute_b32 v120, v156, v115
	ds_bpermute_b32 v121, v156, v114
	v_lshl_add_u64 v[112:113], v[154:155], 2, s[38:39]
	global_store_dwordx4 v[112:113], v[116:119], off
	s_waitcnt lgkmcnt(1)
	v_add_f32_e32 v112, v115, v120
	s_waitcnt lgkmcnt(0)
	v_add_f32_e32 v113, v114, v121
	ds_bpermute_b32 v114, v157, v112
	ds_bpermute_b32 v115, v157, v113
	v_cvt_pk_bf16_f32 v116, v116, v117
	v_cvt_pk_bf16_f32 v117, v118, v119
	v_lshl_add_u64 v[118:119], v[154:155], 1, s[6:7]
	global_store_dwordx2 v[118:119], v[116:117], off
	s_and_saveexec_b64 s[0:1], s[4:5]
	s_cbranch_execz .LBB0_954
	v_lshl_add_u64 v[116:117], s[8:9], 0, v[152:153]
	s_waitcnt lgkmcnt(1)
	v_add_f32_e32 v112, v112, v114
	s_waitcnt lgkmcnt(0)
	v_add_f32_e32 v113, v113, v115
	global_atomic_add_f32 v[116:117], v112, off
	global_atomic_add_f32 v[116:117], v113, off offset:4

; __device__ __forceinline__ f32x2 ln_stats(f32x2 sm) { const float mu = sm[0] * (1.f / D); const float var = fmaxf(sm[1] * (1.f / D) - mu * mu, 0.f); return (f32x2){mu, 1.0f / sqrtf(var + LN_EPS)}; }
;     __device__ __forceinline__ void operator()(const f32x4 (&acc)[2][2][4][2], const Unit& u, int wr, int wc, int fr, int fq) const {
;     ...
;                 f32x4 xv[2][2][2]; f32x2 st[2];
; #pragma unroll
;                 for (int mm = 0; mm < 2; ++mm) {
;                     const int r = row0 + ai * HALF + (2 * m2 + mm) * 16;
;                     st[mm] = (f32x2){0.f, 1.f};
;                     if (rin) st[mm] = ln_stats(*(const f32x2*)(rin + 2 * (size_t)r));
; #pragma unroll
;                     for (int bj = 0; bj < 2; ++bj)
; #pragma unroll
;                         for (int n = 0; n < 2; ++n) { const f32x4* rp = (const f32x4*)(res + (size_t)r * D + col0 + bj * HALF + n * 16); xv[mm][bj][n] = stream ? __builtin_nontemporal_load(rp) : *rp; }
.LBB0_956:
	s_or_b64 exec, exec, s[0:1]
	v_add_u32_e32 v96, 0x80, v194
	v_ashrrev_i32_e32 v97, 31, v96
	v_lshlrev_b64 v[120:121], 3, v[96:97]
	s_waitcnt lgkmcnt(0)
	v_lshl_add_u64 v[98:99], s[54:55], 0, v[120:121]
	global_load_dwordx2 v[140:141], v[98:99], off
	v_lshlrev_b64 v[98:99], 13, v[96:97]
	v_lshl_add_u64 v[142:143], v[192:193], 0, v[98:99]
	global_load_dwordx4 v[124:127], v[142:143], off nt
	global_load_dwordx4 v[128:131], v[142:143], off offset:64 nt
	global_load_dwordx4 v[132:135], v[142:143], off offset:512 nt
	v_add_u32_e32 v118, 0x90, v194
	v_ashrrev_i32_e32 v119, 31, v118
	v_lshlrev_b64 v[112:113], 3, v[118:119]
	v_lshlrev_b64 v[98:99], 13, v[118:119]
	v_lshlrev_b64 v[96:97], 11, v[96:97]
	v_lshl_add_u64 v[100:101], s[54:55], 0, v[112:113]
	v_lshl_add_u64 v[116:117], v[192:193], 0, v[98:99]
	v_lshl_add_u64 v[122:123], v[96:97], 0, v[190:191]
	global_load_dwordx4 v[136:139], v[142:143], off offset:576 nt
	global_load_dwordx2 v[114:115], v[100:101], off
	global_load_dwordx4 v[108:111], v[116:117], off nt
	global_load_dwordx4 v[104:107], v[116:117], off offset:64 nt
	s_nop 0
	global_load_dwordx4 v[100:103], v[116:117], off offset:512 nt
	global_load_dwordx4 v[96:99], v[116:117], off offset:576 nt
	v_lshl_add_u64 v[144:145], v[122:123], 1, s[6:7]
	v_or_b32_e32 v146, 16, v122
	v_mov_b32_e32 v147, v123
	v_lshl_add_u64 v[150:151], v[146:147], 2, s[38:39]
	v_or_b32_e32 v148, 0x80, v122
	v_mov_b32_e32 v149, v123
	v_lshl_add_u64 v[146:147], v[146:147], 1, s[6:7]
	v_or_b32_e32 v122, 0x90, v122
	s_waitcnt vmcnt(9)
	v_pk_mul_f32 v[140:141], v[140:141], s[18:19] op_sel_hi:[1,0]
	s_nop 0
	v_fma_f32 v141, -v140, v140, v141
	v_max_f32_e32 v141, 0, v141
	v_add_f32_e32 v141, 0x3727c5ac, v141
	v_mul_f32_e32 v152, 0x4f800000, v141
	v_cmp_gt_f32_e32 vcc, s52, v141
	s_waitcnt vmcnt(8)
	v_sub_f32_e32 v127, v127, v140
	v_sub_f32_e32 v126, v126, v140
	v_cndmask_b32_e32 v141, v141, v152, vcc
	v_sqrt_f32_e32 v152, v141
	v_sub_f32_e32 v125, v125, v140
	v_sub_f32_e32 v124, v124, v140
	s_waitcnt vmcnt(7)
	v_sub_f32_e32 v131, v131, v140
	v_add_u32_e32 v153, -1, v152
	v_add_u32_e32 v154, 1, v152
	v_fma_f32 v155, -v153, v152, v141
	v_fma_f32 v158, -v154, v152, v141
	v_cmp_ge_f32_e64 s[0:1], 0, v155
	v_sub_f32_e32 v130, v130, v140
	v_sub_f32_e32 v129, v129, v140
	v_cndmask_b32_e64 v152, v152, v153, s[0:1]
	v_cmp_lt_f32_e64 s[0:1], 0, v158
	v_sub_f32_e32 v128, v128, v140
	s_waitcnt vmcnt(6)
; __device__ __forceinline__ unsigned cvt_pk_bf16(float lo, float hi) { unsigned r; asm volatile("v_cvt_pk_bf16_f32 %0, %1, %2" : "=v"(r) : "v"(lo), "v"(hi)); return r; }
;     __device__ __forceinline__ void operator()(const f32x4 (&acc)[2][2][4][2], const Unit& u, int wr, int wc, int fr, int fq) const {
;     ...
;                 for (int mm = 0; mm < 2; ++mm) {
;                     const int r = row0 + ai * HALF + (2 * m2 + mm) * 16;
;                     float ps = 0.f, pq = 0.f;
; #pragma unroll
;                     for (int bj = 0; bj < 2; ++bj)
; #pragma unroll
;                         for (int n = 0; n < 2; ++n) {
;                             const f32x4 x = (xv[mm][bj][n] - st[mm][0]) * (gg[bj][n] * st[mm][1]) + bb[bj][n];
;                             const f32x4 o = x * alpha + acc[ai][bj][2 * m2 + mm][n] * scale;
;                             const size_t off = (size_t)r * D + col0 + bj * HALF + n * 16;
;                             *(f32x4*)(Y + off) = o;
;                             if (yb) { u32x2 w; w.x = cvt_pk_bf16(o[0], o[1]); w.y = cvt_pk_bf16(o[2], o[3]); *(u32x2*)(yb + off) = w; }
;                             ps += (o[0] + o[1]) + (o[2] + o[3]); pq += (o[0] * o[0] + o[1] * o[1]) + (o[2] * o[2] + o[3] * o[3]);
;                         }
;                     if (rout) {
;                         ps += __shfl_xor(ps, 16); pq += __shfl_xor(pq, 16); ps += __shfl_xor(ps, 32); pq += __shfl_xor(pq, 32);
;                         if (fq == 0) { atomicAdd(rout + 2 * (size_t)r, ps); atomicAdd(rout + 2 * (size_t)r + 1, pq); }
	v_sub_f32_e32 v135, v135, v140
	v_cndmask_b32_e64 v152, v152, v154, s[0:1]
	v_mul_f32_e32 v153, 0x37800000, v152
	v_cndmask_b32_e32 v152, v152, v153, vcc
	v_cmp_class_f32_e32 vcc, v141, v212
	v_sub_f32_e32 v134, v134, v140
	v_sub_f32_e32 v133, v133, v140
	v_cndmask_b32_e32 v141, v152, v141, vcc
	v_div_scale_f32 v152, s[0:1], v141, v141, 1.0
	v_rcp_f32_e32 v153, v152
	v_div_scale_f32 v154, vcc, 1.0, v141, 1.0
	v_sub_f32_e32 v132, v132, v140
	v_fma_f32 v155, -v152, v153, 1.0
	v_fmac_f32_e32 v153, v155, v153
	v_mul_f32_e32 v155, v154, v153
	v_fma_f32 v158, -v152, v155, v154
	v_fmac_f32_e32 v155, v158, v153
	v_fma_f32 v152, -v152, v155, v154
	v_div_fmas_f32 v152, v152, v153, v155
	v_div_fixup_f32 v152, v152, v141, 1.0
	v_pk_mul_f32 v[154:155], v[94:95], v[152:153] op_sel_hi:[1,0]
	v_pk_mul_f32 v[158:159], v[92:93], v[152:153] op_sel_hi:[1,0]
	v_pk_mul_f32 v[160:161], v[78:79], v[152:153] op_sel_hi:[1,0]
	v_pk_mul_f32 v[162:163], v[76:77], v[152:153] op_sel_hi:[1,0]
	v_pk_fma_f32 v[124:125], v[124:125], v[158:159], v[88:89]
	v_pk_fma_f32 v[126:127], v[126:127], v[154:155], v[90:91]
	v_pk_mul_f32 v[164:165], v[70:71], v[152:153] op_sel_hi:[1,0]
	v_pk_fma_f32 v[128:129], v[128:129], v[162:163], v[72:73]
	v_pk_fma_f32 v[130:131], v[130:131], v[160:161], v[74:75]
	v_pk_fma_f32 v[86:87], v[126:127], s[20:21], v[86:87] op_sel_hi:[1,0,1]
	v_pk_fma_f32 v[84:85], v[124:125], s[20:21], v[84:85] op_sel_hi:[1,0,1]
	v_pk_fma_f32 v[134:135], v[134:135], v[164:165], v[66:67]
	v_pk_fma_f32 v[82:83], v[130:131], s[20:21], v[82:83] op_sel_hi:[1,0,1]
	v_pk_fma_f32 v[80:81], v[128:129], s[20:21], v[80:81] op_sel_hi:[1,0,1]
	global_store_dwordx4 v[142:143], v[84:87], off
	v_cvt_pk_bf16_f32 v124, v84, v85
	v_add_f32_e32 v126, v84, v85
	v_add_f32_e32 v127, v87, v86
	v_pk_mul_f32 v[166:167], v[68:69], v[152:153] op_sel_hi:[1,0]
	v_pk_fma_f32 v[62:63], v[134:135], s[20:21], v[62:63] op_sel_hi:[1,0,1]
	v_cvt_pk_bf16_f32 v125, v86, v87
	v_mul_f32_e32 v128, v85, v85
	v_mul_f32_e32 v86, v86, v86
	v_add_f32_e32 v129, v80, v81
	v_add_f32_e32 v130, v83, v82
	v_mul_f32_e32 v131, v81, v81
	v_mul_f32_e32 v134, v82, v82
	global_store_dwordx2 v[144:145], v[124:125], off
	v_add_f32_e32 v124, v126, v127
	v_pk_fma_f32 v[132:133], v[132:133], v[166:167], v[64:65]
	v_fmac_f32_e32 v128, v84, v84
	v_fmac_f32_e32 v86, v87, v87
	global_store_dwordx4 v[150:151], v[80:83], off
	v_cvt_pk_bf16_f32 v84, v80, v81
	v_fmac_f32_e32 v131, v80, v80
	v_fmac_f32_e32 v134, v83, v83
	v_add_f32_e32 v81, v129, v130
	v_add_f32_e32 v80, 0, v124
	v_cvt_pk_bf16_f32 v85, v82, v83
	v_add_f32_e32 v82, v128, v86
	global_store_dwordx2 v[146:147], v[84:85], off
	v_add_f32_e32 v83, v131, v134
	v_add_f32_e32 v84, v81, v80
	v_pk_fma_f32 v[60:61], v[132:133], s[20:21], v[60:61] op_sel_hi:[1,0,1]
	v_lshl_add_u64 v[80:81], v[148:149], 2, s[38:39]
	v_add_f32_e32 v85, v82, v83
	global_store_dwordx4 v[80:81], v[60:63], off
	v_cvt_pk_bf16_f32 v80, v60, v61
	v_lshl_add_u64 v[82:83], v[148:149], 1, s[6:7]
	v_cvt_pk_bf16_f32 v81, v62, v63
	global_store_dwordx2 v[82:83], v[80:81], off
	v_add_f32_e32 v80, v60, v61
	v_mul_f32_e32 v61, v61, v61
	v_fmac_f32_e32 v61, v60, v60
	v_mul_f32_e32 v60, v62, v62
	v_add_f32_e32 v81, v63, v62
	v_fmac_f32_e32 v60, v63, v63
	v_add_f32_e32 v80, v80, v81
	v_add_f32_e32 v60, v61, v60
	v_add_f32_e32 v84, v80, v84
	v_add_f32_e32 v85, v60, v85
	s_waitcnt vmcnt(11)
	v_sub_f32_e32 v61, v139, v140
	v_sub_f32_e32 v60, v138, v140
	v_sub_f32_e32 v63, v137, v140
	v_sub_f32_e32 v62, v136, v140
	v_pk_mul_f32 v[80:81], v[58:59], v[152:153] op_sel_hi:[1,0]
	v_pk_mul_f32 v[82:83], v[56:57], v[152:153] op_sel_hi:[1,0]
	v_pk_fma_f32 v[60:61], v[60:61], v[80:81], v[54:55]
	v_pk_fma_f32 v[82:83], v[62:63], v[82:83], v[52:53]
	v_pk_fma_f32 v[62:63], v[60:61], s[20:21], v[50:51] op_sel_hi:[1,0,1]
	v_pk_fma_f32 v[60:61], v[82:83], s[20:21], v[48:49] op_sel_hi:[1,0,1]
	v_mul_f32_e32 v49, v62, v62
	v_mul_f32_e32 v48, v61, v61
	v_fmac_f32_e32 v48, v60, v60
	v_fmac_f32_e32 v49, v63, v63
	v_add_f32_e32 v48, v48, v49
	v_add_f32_e32 v50, v48, v85
	v_add_f32_e32 v48, v60, v61
	v_add_f32_e32 v49, v63, v62
	v_add_f32_e32 v48, v48, v49
	v_add_f32_e32 v51, v48, v84
	ds_bpermute_b32 v80, v156, v51
	ds_bpermute_b32 v81, v156, v50
	v_lshl_add_u64 v[48:49], v[122:123], 2, s[38:39]
	global_store_dwordx4 v[48:49], v[60:63], off
	s_waitcnt lgkmcnt(1)
	v_add_f32_e32 v48, v51, v80
	s_waitcnt lgkmcnt(0)
	v_add_f32_e32 v49, v50, v81
	ds_bpermute_b32 v50, v157, v48
	ds_bpermute_b32 v51, v157, v49
	v_cvt_pk_bf16_f32 v60, v60, v61
	v_cvt_pk_bf16_f32 v61, v62, v63
	v_lshl_add_u64 v[62:63], v[122:123], 1, s[6:7]
	global_store_dwordx2 v[62:63], v[60:61], off
	s_and_saveexec_b64 s[0:1], s[4:5]
	s_cbranch_execz .LBB0_958
	v_lshl_add_u64 v[60:61], s[8:9], 0, v[120:121]
	s_waitcnt lgkmcnt(1)
	v_add_f32_e32 v48, v48, v50
	s_waitcnt lgkmcnt(0)
	v_add_f32_e32 v49, v49, v51
	global_atomic_add_f32 v[60:61], v48, off
	global_atomic_add_f32 v[60:61], v49, off offset:4

; __device__ __forceinline__ unsigned cvt_pk_bf16(float lo, float hi) { unsigned r; asm volatile("v_cvt_pk_bf16_f32 %0, %1, %2" : "=v"(r) : "v"(lo), "v"(hi)); return r; }
;     __device__ __forceinline__ void operator()(const f32x4 (&acc)[2][2][4][2], const Unit& u, int wr, int wc, int fr, int fq) const {
;     ...
;                 f32x4 xv[2][2][2]; f32x2 st[2];
; #pragma unroll
;                 for (int mm = 0; mm < 2; ++mm) {
;                     const int r = row0 + ai * HALF + (2 * m2 + mm) * 16;
;                     st[mm] = (f32x2){0.f, 1.f};
;                     if (rin) st[mm] = ln_stats(*(const f32x2*)(rin + 2 * (size_t)r));
; #pragma unroll
;                     for (int bj = 0; bj < 2; ++bj)
; #pragma unroll
;                         for (int n = 0; n < 2; ++n) { const f32x4* rp = (const f32x4*)(res + (size_t)r * D + col0 + bj * HALF + n * 16); xv[mm][bj][n] = stream ? __builtin_nontemporal_load(rp) : *rp; }
;                 }
; #pragma unroll
;                 for (int mm = 0; mm < 2; ++mm) {
;                     const int r = row0 + ai * HALF + (2 * m2 + mm) * 16;
;                     float ps = 0.f, pq = 0.f;
; #pragma unroll
;                     for (int bj = 0; bj < 2; ++bj)
; #pragma unroll
;                         for (int n = 0; n < 2; ++n) {
;                             const f32x4 x = (xv[mm][bj][n] - st[mm][0]) * (gg[bj][n] * st[mm][1]) + bb[bj][n];
;                             const f32x4 o = x * alpha + acc[ai][bj][2 * m2 + mm][n] * scale;
;                             const size_t off = (size_t)r * D + col0 + bj * HALF + n * 16;
;                             *(f32x4*)(Y + off) = o;
;                             if (yb) { u32x2 w; w.x = cvt_pk_bf16(o[0], o[1]); w.y = cvt_pk_bf16(o[2], o[3]); *(u32x2*)(yb + off) = w; }
;                             ps += (o[0] + o[1]) + (o[2] + o[3]); pq += (o[0] * o[0] + o[1] * o[1]) + (o[2] * o[2] + o[3] * o[3]);
;                         }
;                     if (rout) {
;                         ps += __shfl_xor(ps, 16); pq += __shfl_xor(pq, 16); ps += __shfl_xor(ps, 32); pq += __shfl_xor(pq, 32);
;                         if (fq == 0) { atomicAdd(rout + 2 * (size_t)r, ps); atomicAdd(rout + 2 * (size_t)r + 1, pq); }
.LBB0_960:
	s_or_b64 exec, exec, s[0:1]
	v_add_u32_e32 v32, 0xa0, v194
	v_ashrrev_i32_e32 v33, 31, v32
	v_lshlrev_b64 v[80:81], 3, v[32:33]
	s_waitcnt lgkmcnt(0)
	v_lshl_add_u64 v[34:35], s[54:55], 0, v[80:81]
	global_load_dwordx2 v[108:109], v[34:35], off
	v_lshlrev_b64 v[34:35], 13, v[32:33]
	v_lshl_add_u64 v[110:111], v[192:193], 0, v[34:35]
	global_load_dwordx4 v[84:87], v[110:111], off nt
	global_load_dwordx4 v[96:99], v[110:111], off offset:64 nt
	global_load_dwordx4 v[100:103], v[110:111], off offset:512 nt
	v_add_u32_e32 v62, 0xb0, v194
	v_ashrrev_i32_e32 v63, 31, v62
	v_lshlrev_b64 v[48:49], 3, v[62:63]
	v_lshlrev_b64 v[34:35], 13, v[62:63]
	v_lshlrev_b64 v[32:33], 11, v[32:33]
	v_lshl_add_u64 v[36:37], s[54:55], 0, v[48:49]
	v_lshl_add_u64 v[60:61], v[192:193], 0, v[34:35]
	v_lshl_add_u64 v[82:83], v[32:33], 0, v[190:191]
	global_load_dwordx4 v[104:107], v[110:111], off offset:576 nt
	global_load_dwordx2 v[50:51], v[36:37], off
	global_load_dwordx4 v[44:47], v[60:61], off nt
	global_load_dwordx4 v[40:43], v[60:61], off offset:64 nt
	s_nop 0
	global_load_dwordx4 v[36:39], v[60:61], off offset:512 nt
	global_load_dwordx4 v[32:35], v[60:61], off offset:576 nt
	v_lshl_add_u64 v[112:113], v[82:83], 1, s[6:7]
	v_or_b32_e32 v114, 16, v82
	v_mov_b32_e32 v115, v83
	v_lshl_add_u64 v[118:119], v[114:115], 2, s[38:39]
	v_or_b32_e32 v116, 0x80, v82
	v_mov_b32_e32 v117, v83
	v_lshl_add_u64 v[114:115], v[114:115], 1, s[6:7]
	v_or_b32_e32 v82, 0x90, v82
	s_waitcnt vmcnt(9)
	v_pk_mul_f32 v[108:109], v[108:109], s[18:19] op_sel_hi:[1,0]
	s_nop 0
	v_fma_f32 v109, -v108, v108, v109
	v_max_f32_e32 v109, 0, v109
	v_add_f32_e32 v109, 0x3727c5ac, v109
	v_mul_f32_e32 v120, 0x4f800000, v109
	v_cmp_gt_f32_e32 vcc, s52, v109
	s_waitcnt vmcnt(8)
	v_sub_f32_e32 v87, v87, v108
	v_sub_f32_e32 v86, v86, v108
	v_cndmask_b32_e32 v109, v109, v120, vcc
	v_sqrt_f32_e32 v120, v109
	v_sub_f32_e32 v85, v85, v108
	v_sub_f32_e32 v84, v84, v108
	s_waitcnt vmcnt(7)
	v_sub_f32_e32 v99, v99, v108
	v_add_u32_e32 v121, -1, v120
	v_add_u32_e32 v122, 1, v120
	v_fma_f32 v123, -v121, v120, v109
	v_fma_f32 v124, -v122, v120, v109
	v_cmp_ge_f32_e64 s[0:1], 0, v123
	v_sub_f32_e32 v98, v98, v108
	v_sub_f32_e32 v97, v97, v108
	v_cndmask_b32_e64 v120, v120, v121, s[0:1]
	v_cmp_lt_f32_e64 s[0:1], 0, v124
	v_sub_f32_e32 v96, v96, v108
	s_waitcnt vmcnt(6)
	v_sub_f32_e32 v103, v103, v108
	v_cndmask_b32_e64 v120, v120, v122, s[0:1]
	v_mul_f32_e32 v121, 0x37800000, v120
	v_cndmask_b32_e32 v120, v120, v121, vcc
	v_cmp_class_f32_e32 vcc, v109, v212
	v_sub_f32_e32 v102, v102, v108
	v_sub_f32_e32 v101, v101, v108
	v_cndmask_b32_e32 v109, v120, v109, vcc
	v_div_scale_f32 v120, s[0:1], v109, v109, 1.0
	v_rcp_f32_e32 v121, v120
	v_div_scale_f32 v122, vcc, 1.0, v109, 1.0
	v_sub_f32_e32 v100, v100, v108
	v_fma_f32 v123, -v120, v121, 1.0
	v_fmac_f32_e32 v121, v123, v121
	v_mul_f32_e32 v123, v122, v121
	v_fma_f32 v124, -v120, v123, v122
	v_fmac_f32_e32 v123, v124, v121
	v_fma_f32 v120, -v120, v123, v122
	v_div_fmas_f32 v120, v120, v121, v123
	v_div_fixup_f32 v120, v120, v109, 1.0
	v_pk_mul_f32 v[122:123], v[94:95], v[120:121] op_sel_hi:[1,0]
	v_pk_mul_f32 v[124:125], v[92:93], v[120:121] op_sel_hi:[1,0]
	v_pk_mul_f32 v[126:127], v[78:79], v[120:121] op_sel_hi:[1,0]
	v_pk_mul_f32 v[128:129], v[76:77], v[120:121] op_sel_hi:[1,0]
	v_pk_fma_f32 v[84:85], v[84:85], v[124:125], v[88:89]
	v_pk_fma_f32 v[86:87], v[86:87], v[122:123], v[90:91]
	v_pk_mul_f32 v[130:131], v[70:71], v[120:121] op_sel_hi:[1,0]
	v_pk_fma_f32 v[96:97], v[96:97], v[128:129], v[72:73]
	v_pk_fma_f32 v[98:99], v[98:99], v[126:127], v[74:75]
	v_pk_fma_f32 v[30:31], v[86:87], s[20:21], v[30:31] op_sel_hi:[1,0,1]
	v_pk_fma_f32 v[28:29], v[84:85], s[20:21], v[28:29] op_sel_hi:[1,0,1]
	v_pk_fma_f32 v[102:103], v[102:103], v[130:131], v[66:67]
	v_pk_fma_f32 v[26:27], v[98:99], s[20:21], v[26:27] op_sel_hi:[1,0,1]
	v_pk_fma_f32 v[24:25], v[96:97], s[20:21], v[24:25] op_sel_hi:[1,0,1]
	global_store_dwordx4 v[110:111], v[28:31], off
	v_cvt_pk_bf16_f32 v84, v28, v29
	v_add_f32_e32 v86, v28, v29
	v_add_f32_e32 v87, v31, v30
	v_pk_mul_f32 v[132:133], v[68:69], v[120:121] op_sel_hi:[1,0]
	v_pk_fma_f32 v[22:23], v[102:103], s[20:21], v[22:23] op_sel_hi:[1,0,1]
	v_cvt_pk_bf16_f32 v85, v30, v31
	v_mul_f32_e32 v96, v29, v29
	v_mul_f32_e32 v30, v30, v30
	v_add_f32_e32 v97, v24, v25
	v_add_f32_e32 v98, v27, v26
	v_mul_f32_e32 v99, v25, v25
	v_mul_f32_e32 v102, v26, v26
	global_store_dwordx2 v[112:113], v[84:85], off
	v_add_f32_e32 v84, v86, v87
	v_pk_fma_f32 v[100:101], v[100:101], v[132:133], v[64:65]
	v_fmac_f32_e32 v96, v28, v28
	v_fmac_f32_e32 v30, v31, v31
	global_store_dwordx4 v[118:119], v[24:27], off
	v_cvt_pk_bf16_f32 v28, v24, v25
	v_fmac_f32_e32 v99, v24, v24
	v_fmac_f32_e32 v102, v27, v27
	v_add_f32_e32 v25, v97, v98
	v_add_f32_e32 v24, 0, v84
	v_cvt_pk_bf16_f32 v29, v26, v27
	v_add_f32_e32 v26, v96, v30
	global_store_dwordx2 v[114:115], v[28:29], off
	v_add_f32_e32 v27, v99, v102
	v_add_f32_e32 v28, v25, v24
	v_pk_fma_f32 v[20:21], v[100:101], s[20:21], v[20:21] op_sel_hi:[1,0,1]
	v_lshl_add_u64 v[24:25], v[116:117], 2, s[38:39]
	v_add_f32_e32 v29, v26, v27
	global_store_dwordx4 v[24:25], v[20:23], off
	v_cvt_pk_bf16_f32 v24, v20, v21
	v_lshl_add_u64 v[26:27], v[116:117], 1, s[6:7]
	v_cvt_pk_bf16_f32 v25, v22, v23
	global_store_dwordx2 v[26:27], v[24:25], off
	v_add_f32_e32 v24, v20, v21
	v_mul_f32_e32 v21, v21, v21
	v_fmac_f32_e32 v21, v20, v20
	v_mul_f32_e32 v20, v22, v22
	v_add_f32_e32 v25, v23, v22
	v_fmac_f32_e32 v20, v23, v23
	v_add_f32_e32 v24, v24, v25
	v_add_f32_e32 v20, v21, v20
	v_add_f32_e32 v28, v24, v28
	v_add_f32_e32 v29, v20, v29
	s_waitcnt vmcnt(11)
	v_sub_f32_e32 v21, v107, v108
	v_sub_f32_e32 v20, v106, v108
	v_sub_f32_e32 v23, v105, v108
	v_sub_f32_e32 v22, v104, v108
	v_pk_mul_f32 v[24:25], v[58:59], v[120:121] op_sel_hi:[1,0]
	v_pk_mul_f32 v[26:27], v[56:57], v[120:121] op_sel_hi:[1,0]
	v_pk_fma_f32 v[20:21], v[20:21], v[24:25], v[54:55]
	v_pk_fma_f32 v[26:27], v[22:23], v[26:27], v[52:53]
	v_pk_fma_f32 v[22:23], v[20:21], s[20:21], v[18:19] op_sel_hi:[1,0,1]
	v_pk_fma_f32 v[20:21], v[26:27], s[20:21], v[16:17] op_sel_hi:[1,0,1]
	v_mul_f32_e32 v17, v22, v22
	v_mul_f32_e32 v16, v21, v21
	v_fmac_f32_e32 v16, v20, v20
	v_fmac_f32_e32 v17, v23, v23
	v_add_f32_e32 v16, v16, v17
	v_add_f32_e32 v18, v16, v29
	v_add_f32_e32 v16, v20, v21
	v_add_f32_e32 v17, v23, v22
	v_add_f32_e32 v16, v16, v17
	v_add_f32_e32 v19, v16, v28
	ds_bpermute_b32 v24, v156, v19
	ds_bpermute_b32 v25, v156, v18
	v_lshl_add_u64 v[16:17], v[82:83], 2, s[38:39]
	global_store_dwordx4 v[16:17], v[20:23], off
	s_waitcnt lgkmcnt(1)
	v_add_f32_e32 v16, v19, v24
	s_waitcnt lgkmcnt(0)
	v_add_f32_e32 v17, v18, v25
	ds_bpermute_b32 v18, v157, v16
	ds_bpermute_b32 v19, v157, v17
	v_cvt_pk_bf16_f32 v20, v20, v21
	v_cvt_pk_bf16_f32 v21, v22, v23
	v_lshl_add_u64 v[22:23], v[82:83], 1, s[6:7]
	global_store_dwordx2 v[22:23], v[20:21], off
	s_and_saveexec_b64 s[0:1], s[4:5]
	s_cbranch_execz .LBB0_962
;     __device__ __forceinline__ void operator()(const f32x4 (&acc)[2][2][4][2], const Unit& u, int wr, int wc, int fr, int fq) const {
;     ...
;                     if (rout) {
;                         ps += __shfl_xor(ps, 16); pq += __shfl_xor(pq, 16); ps += __shfl_xor(ps, 32); pq += __shfl_xor(pq, 32);
;                         if (fq == 0) { atomicAdd(rout + 2 * (size_t)r, ps); atomicAdd(rout + 2 * (size_t)r + 1, pq); }
	v_lshl_add_u64 v[20:21], s[8:9], 0, v[80:81]
	s_waitcnt lgkmcnt(1)
	v_add_f32_e32 v16, v16, v18
	s_waitcnt lgkmcnt(0)
	v_add_f32_e32 v17, v17, v19
	global_atomic_add_f32 v[20:21], v16, off
	global_atomic_add_f32 v[20:21], v17, off offset:4

; __device__ __forceinline__ f32x2 ln_stats(f32x2 sm) { const float mu = sm[0] * (1.f / D); const float var = fmaxf(sm[1] * (1.f / D) - mu * mu, 0.f); return (f32x2){mu, 1.0f / sqrtf(var + LN_EPS)}; }
;     __device__ __forceinline__ void operator()(const f32x4 (&acc)[2][2][4][2], const Unit& u, int wr, int wc, int fr, int fq) const {
;     ...
;                 f32x4 xv[2][2][2]; f32x2 st[2];
; #pragma unroll
;                 for (int mm = 0; mm < 2; ++mm) {
;                     const int r = row0 + ai * HALF + (2 * m2 + mm) * 16;
;                     st[mm] = (f32x2){0.f, 1.f};
;                     if (rin) st[mm] = ln_stats(*(const f32x2*)(rin + 2 * (size_t)r));
; #pragma unroll
;                     for (int bj = 0; bj < 2; ++bj)
; #pragma unroll
;                         for (int n = 0; n < 2; ++n) { const f32x4* rp = (const f32x4*)(res + (size_t)r * D + col0 + bj * HALF + n * 16); xv[mm][bj][n] = stream ? __builtin_nontemporal_load(rp) : *rp; }
;                 }
; #pragma unroll
;                 for (int mm = 0; mm < 2; ++mm) {
;                     const int r = row0 + ai * HALF + (2 * m2 + mm) * 16;
;                     float ps = 0.f, pq = 0.f;
; #pragma unroll
;                     for (int bj = 0; bj < 2; ++bj)
; #pragma unroll
;                         for (int n = 0; n < 2; ++n) {
;                             const f32x4 x = (xv[mm][bj][n] - st[mm][0]) * (gg[bj][n] * st[mm][1]) + bb[bj][n];
;                             const f32x4 o = x * alpha + acc[ai][bj][2 * m2 + mm][n] * scale;
;                             const size_t off = (size_t)r * D + col0 + bj * HALF + n * 16;
;                             *(f32x4*)(Y + off) = o;
.LBB0_1123:
	v_mbcnt_lo_u32_b32 v246, -1, 0
	v_mbcnt_hi_u32_b32 v246, -1, v246
	v_lshrrev_b32_e32 v247, 2, v246
	v_and_b32_e32 v248, 3, v246
	v_lshl_add_u32 v238, v248, 4, v247
	v_lshlrev_b32_e32 v238, 2, v238
	v_and_b32_e32 v249, 15, v246
	v_sub_u32_e32 v247, v247, v249
	v_lshrrev_b32_e32 v249, 4, v246
	v_sub_u32_e32 v248, v248, v249
	v_mul_i32_i24_e32 v240, 0x2000, v247
	v_lshl_add_u32 v240, v248, 4, v240
	v_ashrrev_i32_e32 v241, 31, v240
	v_mul_i32_i24_e32 v242, 0x1000, v247
	v_lshl_add_u32 v242, v248, 3, v242
	v_ashrrev_i32_e32 v243, 31, v242
	v_lshl_or_b32 v96, s48, 8, v177
	v_lshl_add_u32 v172, s47, 8, v174
	v_ashrrev_i32_e32 v97, 31, v96
	v_ashrrev_i32_e32 v173, 31, v172
	v_lshlrev_b64 v[168:169], 2, v[96:97]
	v_lshl_add_u64 v[96:97], v[172:173], 3, s[8:9]
	global_load_dwordx2 v[216:217], v[96:97], off
	v_or_b32_e32 v98, 16, v172
	v_ashrrev_i32_e32 v99, 31, v98
	v_lshl_add_u64 v[170:171], s[38:39], 0, v[168:169]
	v_lshlrev_b64 v[96:97], 13, v[172:173]
	v_lshl_add_u64 v[100:101], v[98:99], 3, s[8:9]
	v_lshl_add_u64 v[196:197], v[170:171], 0, v[96:97]
	global_load_dwordx2 v[218:219], v[100:101], off
	global_load_dwordx4 v[184:187], v[196:197], off
	global_load_dwordx4 v[188:191], v[196:197], off offset:64
	global_load_dwordx4 v[192:195], v[196:197], off offset:576
	v_readlane_b32 s48, v254, 27
	v_readlane_b32 s50, v254, 29
	v_readlane_b32 s51, v254, 30
	v_readlane_b32 s58, v254, 37
	v_readlane_b32 s59, v254, 38
	v_readlane_b32 s52, v254, 31
	v_readlane_b32 s53, v254, 32
	v_readlane_b32 s60, v254, 39
	v_readlane_b32 s61, v254, 40
	s_mov_b64 s[50:51], s[58:59]
	s_mov_b64 s[52:53], s[60:61]
	v_lshl_add_u64 v[100:101], s[50:51], 0, v[168:169]
	v_lshl_add_u64 v[198:199], s[52:53], 0, v[168:169]
	v_lshlrev_b64 v[220:221], 13, v[98:99]
	v_lshl_add_u64 v[200:201], s[38:39], 0, v[96:97]
	global_load_dwordx4 v[124:127], v[100:101], off
	global_load_dwordx4 v[116:119], v[100:101], off offset:64
	global_load_dwordx4 v[120:123], v[198:199], off
	global_load_dwordx4 v[112:115], v[198:199], off offset:64
	global_load_dwordx4 v[108:111], v[100:101], off offset:512
	s_nop 0
	global_load_dwordx4 v[100:103], v[100:101], off offset:576 nt
	s_nop 0
	global_load_dwordx4 v[104:107], v[198:199], off offset:512 nt
	global_load_dwordx4 v[96:99], v[198:199], off offset:576 nt
	v_lshl_add_u64 v[212:213], v[170:171], 0, v[220:221]
	v_lshl_add_u64 v[222:223], v[200:201], 0, v[168:169]
	global_load_dwordx4 v[196:199], v[196:197], off offset:512 nt
	s_nop 0
	global_load_dwordx4 v[200:203], v[212:213], off nt
	global_load_dwordx4 v[204:207], v[212:213], off offset:64 nt
	global_load_dwordx4 v[208:211], v[212:213], off offset:512 nt
	s_nop 0
	global_load_dwordx4 v[212:215], v[212:213], off offset:576 nt
	v_readlane_b32 s49, v254, 28
	v_readlane_b32 s54, v254, 33
	v_readlane_b32 s55, v254, 34
	v_readlane_b32 s56, v254, 35
	v_readlane_b32 s57, v254, 36
	v_readlane_b32 s62, v254, 41
	v_readlane_b32 s63, v254, 42
	s_waitcnt vmcnt(0)
	v_pk_mul_f32 v[216:217], v[216:217], s[14:15] op_sel_hi:[1,0]
	s_nop 0
	v_fma_f32 v173, -v216, v216, v217
	v_max_f32_e32 v173, 0, v173
	v_add_f32_e32 v173, 0x3727c5ac, v173
	v_pk_mul_f32 v[218:219], v[218:219], s[14:15] op_sel_hi:[1,0]
	v_mul_f32_e32 v217, 0x4f800000, v173
	v_fma_f32 v183, -v218, v218, v219
	v_cmp_gt_f32_e32 vcc, s44, v173
	v_max_f32_e32 v183, 0, v183
	v_add_f32_e32 v183, 0x3727c5ac, v183
	v_cndmask_b32_e32 v173, v173, v217, vcc
	v_sqrt_f32_e32 v217, v173
	v_mul_f32_e32 v219, 0x4f800000, v183
	v_cmp_gt_f32_e64 s[0:1], s44, v183
	v_sub_f32_e32 v185, v185, v216
	v_add_u32_e32 v224, -1, v217
	v_cndmask_b32_e64 v183, v183, v219, s[0:1]
	v_sqrt_f32_e32 v219, v183
	v_add_u32_e32 v225, 1, v217
	v_fma_f32 v226, -v224, v217, v173
	v_fma_f32 v227, -v225, v217, v173
	v_cmp_ge_f32_e64 s[4:5], 0, v226
	v_add_u32_e32 v226, 1, v219
	v_sub_f32_e32 v184, v184, v216
	v_cndmask_b32_e64 v217, v217, v224, s[4:5]
	v_add_u32_e32 v224, -1, v219
	v_cmp_lt_f32_e64 s[4:5], 0, v227
	v_fma_f32 v227, -v226, v219, v183
	v_sub_f32_e32 v187, v187, v216
	v_cndmask_b32_e64 v217, v217, v225, s[4:5]
	v_fma_f32 v225, -v224, v219, v183
	v_mul_f32_e32 v228, 0x37800000, v217
	v_cmp_ge_f32_e64 s[4:5], 0, v225
	v_cndmask_b32_e32 v217, v217, v228, vcc
	v_cmp_lt_f32_e32 vcc, 0, v227
	v_cndmask_b32_e64 v219, v219, v224, s[4:5]
	v_sub_f32_e32 v186, v186, v216
	v_cndmask_b32_e32 v219, v219, v226, vcc
	v_cmp_class_f32_e32 vcc, v173, v182
	v_sub_f32_e32 v189, v189, v216
	v_sub_f32_e32 v188, v188, v216
	v_cndmask_b32_e32 v173, v217, v173, vcc
	v_mul_f32_e32 v217, 0x37800000, v219
	v_div_scale_f32 v224, s[4:5], v173, v173, 1.0
	v_cndmask_b32_e64 v217, v219, v217, s[0:1]
	v_cmp_class_f32_e64 s[0:1], v183, v182
	v_rcp_f32_e32 v219, v224
	v_div_scale_f32 v225, vcc, 1.0, v173, 1.0
	v_cndmask_b32_e64 v183, v217, v183, s[0:1]
	v_div_scale_f32 v217, s[0:1], v183, v183, 1.0
	v_rcp_f32_e32 v227, v217
	v_fma_f32 v228, -v224, v219, 1.0
	v_fmac_f32_e32 v219, v228, v219
	v_mul_f32_e32 v228, v225, v219
	v_fma_f32 v229, -v217, v227, 1.0
	v_div_scale_f32 v226, s[0:1], 1.0, v183, 1.0
	v_fma_f32 v230, -v224, v228, v225
	v_fmac_f32_e32 v227, v229, v227
	v_fmac_f32_e32 v228, v230, v219
	v_mul_f32_e32 v229, v226, v227
	v_fma_f32 v224, -v224, v228, v225
	v_fma_f32 v225, -v217, v229, v226
	v_div_fmas_f32 v219, v224, v219, v228
	v_fmac_f32_e32 v229, v225, v227
	v_div_fixup_f32 v224, v219, v173, 1.0
	v_fma_f32 v173, -v217, v229, v226
	s_mov_b64 vcc, s[0:1]
	v_div_fmas_f32 v173, v173, v227, v229
	v_pk_mul_f32 v[226:227], v[124:125], v[224:225] op_sel_hi:[1,0]
	v_pk_mul_f32 v[228:229], v[126:127], v[224:225] op_sel_hi:[1,0]
	v_pk_fma_f32 v[184:185], v[184:185], v[226:227], v[120:121]
	v_pk_fma_f32 v[186:187], v[186:187], v[228:229], v[122:123]
	v_pk_mul_f32 v[184:185], v[184:185], s[16:17] op_sel_hi:[1,0]
	v_pk_mul_f32 v[186:187], v[186:187], s[16:17] op_sel_hi:[1,0]
	v_pk_fma_f32 v[156:157], v[156:157], 0.5, v[184:185] op_sel_hi:[1,0,1]
	v_pk_fma_f32 v[158:159], v[158:159], 0.5, v[186:187] op_sel_hi:[1,0,1]
	ds_bpermute_b32 v246, v238, v156
	ds_bpermute_b32 v247, v238, v157
	ds_bpermute_b32 v248, v238, v158
	ds_bpermute_b32 v249, v238, v159
	v_lshl_add_u64 v[244:245], v[222:223], 0, v[240:241]
	s_waitcnt lgkmcnt(0)
;     __device__ __forceinline__ void operator()(const f32x4 (&acc)[2][2][4][2], const Unit& u, int wr, int wc, int fr, int fq) const {
;     ...
;                 for (int mm = 0; mm < 2; ++mm) {
;                     const int r = row0 + ai * HALF + (2 * m2 + mm) * 16;
;                     float ps = 0.f, pq = 0.f;
; #pragma unroll
;                     for (int bj = 0; bj < 2; ++bj)
; #pragma unroll
;                         for (int n = 0; n < 2; ++n) {
;                             const f32x4 x = (xv[mm][bj][n] - st[mm][0]) * (gg[bj][n] * st[mm][1]) + bb[bj][n];
;                             const f32x4 o = x * alpha + acc[ai][bj][2 * m2 + mm][n] * scale;
;                             const size_t off = (size_t)r * D + col0 + bj * HALF + n * 16;
;                             *(f32x4*)(Y + off) = o;
	global_store_dwordx4 v[244:245], v[246:249], off
	v_pk_mul_f32 v[184:185], v[118:119], v[224:225] op_sel_hi:[1,0]
	v_div_fixup_f32 v230, v173, v183, 1.0
	v_sub_f32_e32 v157, v191, v216
	v_sub_f32_e32 v156, v190, v216
	v_pk_mul_f32 v[158:159], v[116:117], v[224:225] op_sel_hi:[1,0]
	v_pk_fma_f32 v[156:157], v[156:157], v[184:185], v[114:115]
	v_pk_fma_f32 v[158:159], v[188:189], v[158:159], v[112:113]
	v_pk_mul_f32 v[156:157], v[156:157], s[16:17] op_sel_hi:[1,0]
	v_pk_mul_f32 v[158:159], v[158:159], s[16:17] op_sel_hi:[1,0]
	v_pk_fma_f32 v[154:155], v[154:155], 0.5, v[156:157] op_sel_hi:[1,0,1]
	v_pk_fma_f32 v[152:153], v[152:153], 0.5, v[158:159] op_sel_hi:[1,0,1]
	ds_bpermute_b32 v250, v238, v152
	ds_bpermute_b32 v251, v238, v153
	ds_bpermute_b32 v252, v238, v154
	ds_bpermute_b32 v253, v238, v155
	v_lshl_add_u64 v[244:245], v[222:223], 0, v[240:241]
	s_waitcnt lgkmcnt(0)
	global_store_dwordx4 v[244:245], v[250:253], off offset:64
	v_pk_mul_f32 v[156:157], v[108:109], v[224:225] op_sel_hi:[1,0]
	v_pk_mul_f32 v[158:159], v[110:111], v[224:225] op_sel_hi:[1,0]
	v_sub_f32_e32 v153, v197, v216
	v_sub_f32_e32 v152, v196, v216
	v_sub_f32_e32 v155, v199, v216
	v_sub_f32_e32 v154, v198, v216
	v_pk_fma_f32 v[154:155], v[154:155], v[158:159], v[106:107]
	v_pk_fma_f32 v[152:153], v[152:153], v[156:157], v[104:105]
	v_pk_mul_f32 v[154:155], v[154:155], s[16:17] op_sel_hi:[1,0]
	v_pk_mul_f32 v[152:153], v[152:153], s[16:17] op_sel_hi:[1,0]
	v_pk_fma_f32 v[150:151], v[150:151], 0.5, v[154:155] op_sel_hi:[1,0,1]
	v_pk_fma_f32 v[148:149], v[148:149], 0.5, v[152:153] op_sel_hi:[1,0,1]
	ds_bpermute_b32 v246, v238, v148
	ds_bpermute_b32 v247, v238, v149
	ds_bpermute_b32 v248, v238, v150
	ds_bpermute_b32 v249, v238, v151
	v_lshl_add_u64 v[244:245], v[222:223], 0, v[240:241]
	s_waitcnt lgkmcnt(0)
	global_store_dwordx4 v[244:245], v[246:249], off offset:512
	v_pk_mul_f32 v[152:153], v[100:101], v[224:225] op_sel_hi:[1,0]
	v_pk_mul_f32 v[154:155], v[102:103], v[224:225] op_sel_hi:[1,0]
	v_sub_f32_e32 v149, v193, v216
	v_sub_f32_e32 v148, v192, v216
	v_sub_f32_e32 v151, v195, v216
	v_sub_f32_e32 v150, v194, v216
	v_pk_fma_f32 v[150:151], v[150:151], v[154:155], v[98:99]
	v_pk_fma_f32 v[148:149], v[148:149], v[152:153], v[96:97]
	v_pk_mul_f32 v[150:151], v[150:151], s[16:17] op_sel_hi:[1,0]
	v_pk_mul_f32 v[148:149], v[148:149], s[16:17] op_sel_hi:[1,0]
	v_pk_fma_f32 v[142:143], v[142:143], 0.5, v[150:151] op_sel_hi:[1,0,1]
	v_pk_fma_f32 v[140:141], v[140:141], 0.5, v[148:149] op_sel_hi:[1,0,1]
	ds_bpermute_b32 v250, v238, v140
	ds_bpermute_b32 v251, v238, v141
	ds_bpermute_b32 v252, v238, v142
	ds_bpermute_b32 v253, v238, v143
	v_lshl_add_u64 v[244:245], v[222:223], 0, v[240:241]
	s_waitcnt lgkmcnt(0)
	global_store_dwordx4 v[244:245], v[250:253], off offset:576
	v_pk_mul_f32 v[148:149], v[124:125], v[230:231] op_sel_hi:[1,0]
	v_pk_mul_f32 v[150:151], v[126:127], v[230:231] op_sel_hi:[1,0]
	v_sub_f32_e32 v141, v201, v218
	v_sub_f32_e32 v140, v200, v218
	v_sub_f32_e32 v143, v203, v218
	v_sub_f32_e32 v142, v202, v218
	v_pk_fma_f32 v[140:141], v[140:141], v[148:149], v[120:121]
	v_pk_fma_f32 v[142:143], v[142:143], v[150:151], v[122:123]
	v_pk_mul_f32 v[140:141], v[140:141], s[16:17] op_sel_hi:[1,0]
	v_pk_mul_f32 v[142:143], v[142:143], s[16:17] op_sel_hi:[1,0]
	v_pk_fma_f32 v[140:141], v[144:145], 0.5, v[140:141] op_sel_hi:[1,0,1]
	v_lshl_add_u64 v[144:145], s[38:39], 0, v[220:221]
	v_pk_fma_f32 v[142:143], v[146:147], 0.5, v[142:143] op_sel_hi:[1,0,1]
	v_lshl_add_u64 v[144:145], v[144:145], 0, v[168:169]
	ds_bpermute_b32 v246, v238, v140
	ds_bpermute_b32 v247, v238, v141
	ds_bpermute_b32 v248, v238, v142
	ds_bpermute_b32 v249, v238, v143
	v_lshl_add_u64 v[244:245], v[144:145], 0, v[240:241]
	s_waitcnt lgkmcnt(0)
	global_store_dwordx4 v[244:245], v[246:249], off
	v_pk_mul_f32 v[146:147], v[116:117], v[230:231] op_sel_hi:[1,0]
	v_pk_mul_f32 v[148:149], v[118:119], v[230:231] op_sel_hi:[1,0]
	v_sub_f32_e32 v141, v205, v218
	v_sub_f32_e32 v140, v204, v218
	v_sub_f32_e32 v143, v207, v218
	v_sub_f32_e32 v142, v206, v218
	v_pk_fma_f32 v[142:143], v[142:143], v[148:149], v[114:115]
	v_pk_fma_f32 v[140:141], v[140:141], v[146:147], v[112:113]
	v_pk_mul_f32 v[142:143], v[142:143], s[16:17] op_sel_hi:[1,0]
	v_pk_mul_f32 v[140:141], v[140:141], s[16:17] op_sel_hi:[1,0]
	v_pk_fma_f32 v[138:139], v[138:139], 0.5, v[142:143] op_sel_hi:[1,0,1]
	v_pk_fma_f32 v[136:137], v[136:137], 0.5, v[140:141] op_sel_hi:[1,0,1]
	ds_bpermute_b32 v250, v238, v136
	ds_bpermute_b32 v251, v238, v137
	ds_bpermute_b32 v252, v238, v138
	ds_bpermute_b32 v253, v238, v139
	v_lshl_add_u64 v[244:245], v[144:145], 0, v[240:241]
	s_waitcnt lgkmcnt(0)
	global_store_dwordx4 v[244:245], v[250:253], off offset:64
	v_pk_mul_f32 v[140:141], v[108:109], v[230:231] op_sel_hi:[1,0]
	v_pk_mul_f32 v[142:143], v[110:111], v[230:231] op_sel_hi:[1,0]
	v_sub_f32_e32 v137, v209, v218
	v_sub_f32_e32 v136, v208, v218
	v_sub_f32_e32 v139, v211, v218
	v_sub_f32_e32 v138, v210, v218
	v_pk_fma_f32 v[138:139], v[138:139], v[142:143], v[106:107]
	v_pk_fma_f32 v[136:137], v[136:137], v[140:141], v[104:105]
	v_pk_mul_f32 v[138:139], v[138:139], s[16:17] op_sel_hi:[1,0]
	v_pk_mul_f32 v[136:137], v[136:137], s[16:17] op_sel_hi:[1,0]
	v_pk_fma_f32 v[134:135], v[134:135], 0.5, v[138:139] op_sel_hi:[1,0,1]
	v_pk_fma_f32 v[132:133], v[132:133], 0.5, v[136:137] op_sel_hi:[1,0,1]
	ds_bpermute_b32 v246, v238, v132
	ds_bpermute_b32 v247, v238, v133
	ds_bpermute_b32 v248, v238, v134
	ds_bpermute_b32 v249, v238, v135
	v_lshl_add_u64 v[244:245], v[144:145], 0, v[240:241]
	s_waitcnt lgkmcnt(0)
; __device__ __forceinline__ f32x2 ln_stats(f32x2 sm) { const float mu = sm[0] * (1.f / D); const float var = fmaxf(sm[1] * (1.f / D) - mu * mu, 0.f); return (f32x2){mu, 1.0f / sqrtf(var + LN_EPS)}; }
;     __device__ __forceinline__ void operator()(const f32x4 (&acc)[2][2][4][2], const Unit& u, int wr, int wc, int fr, int fq) const {
;     ...
;                 f32x4 xv[2][2][2]; f32x2 st[2];
; #pragma unroll
;                 for (int mm = 0; mm < 2; ++mm) {
;                     const int r = row0 + ai * HALF + (2 * m2 + mm) * 16;
;                     st[mm] = (f32x2){0.f, 1.f};
;                     if (rin) st[mm] = ln_stats(*(const f32x2*)(rin + 2 * (size_t)r));
; #pragma unroll
;                     for (int bj = 0; bj < 2; ++bj)
; #pragma unroll
;                         for (int n = 0; n < 2; ++n) { const f32x4* rp = (const f32x4*)(res + (size_t)r * D + col0 + bj * HALF + n * 16); xv[mm][bj][n] = stream ? __builtin_nontemporal_load(rp) : *rp; }
;                 }
; #pragma unroll
;                 for (int mm = 0; mm < 2; ++mm) {
;                     const int r = row0 + ai * HALF + (2 * m2 + mm) * 16;
;                     float ps = 0.f, pq = 0.f;
; #pragma unroll
;                     for (int bj = 0; bj < 2; ++bj)
; #pragma unroll
;                         for (int n = 0; n < 2; ++n) {
;                             const f32x4 x = (xv[mm][bj][n] - st[mm][0]) * (gg[bj][n] * st[mm][1]) + bb[bj][n];
;                             const f32x4 o = x * alpha + acc[ai][bj][2 * m2 + mm][n] * scale;
;                             const size_t off = (size_t)r * D + col0 + bj * HALF + n * 16;
;                             *(f32x4*)(Y + off) = o;
	global_store_dwordx4 v[244:245], v[246:249], off offset:512
	v_pk_mul_f32 v[136:137], v[100:101], v[230:231] op_sel_hi:[1,0]
	v_pk_mul_f32 v[138:139], v[102:103], v[230:231] op_sel_hi:[1,0]
	v_sub_f32_e32 v133, v213, v218
	v_sub_f32_e32 v132, v212, v218
	v_sub_f32_e32 v135, v215, v218
	v_sub_f32_e32 v134, v214, v218
	v_pk_fma_f32 v[134:135], v[134:135], v[138:139], v[98:99]
	v_pk_fma_f32 v[132:133], v[132:133], v[136:137], v[96:97]
	v_pk_mul_f32 v[134:135], v[134:135], s[16:17] op_sel_hi:[1,0]
	v_pk_mul_f32 v[132:133], v[132:133], s[16:17] op_sel_hi:[1,0]
	v_pk_fma_f32 v[130:131], v[130:131], 0.5, v[134:135] op_sel_hi:[1,0,1]
	v_pk_fma_f32 v[128:129], v[128:129], 0.5, v[132:133] op_sel_hi:[1,0,1]
	ds_bpermute_b32 v250, v238, v128
	ds_bpermute_b32 v251, v238, v129
	ds_bpermute_b32 v252, v238, v130
	ds_bpermute_b32 v253, v238, v131
	v_lshl_add_u64 v[244:245], v[144:145], 0, v[240:241]
	s_waitcnt lgkmcnt(0)
	global_store_dwordx4 v[244:245], v[250:253], off offset:576
	v_or_b32_e32 v144, 48, v172
	v_ashrrev_i32_e32 v145, 31, v144
	v_or_b32_e32 v128, 32, v172
	v_ashrrev_i32_e32 v129, 31, v128
	v_lshl_add_u64 v[130:131], v[128:129], 3, s[8:9]
	global_load_dwordx2 v[132:133], v[130:131], off
	v_lshl_add_u64 v[130:131], v[144:145], 3, s[8:9]
	global_load_dwordx2 v[146:147], v[130:131], off
	v_lshlrev_b64 v[184:185], 13, v[128:129]
	v_lshl_add_u64 v[140:141], v[170:171], 0, v[184:185]
	v_lshlrev_b64 v[190:191], 13, v[144:145]
	v_lshl_add_u64 v[156:157], v[170:171], 0, v[190:191]
	s_waitcnt vmcnt(1)
	v_pk_mul_f32 v[186:187], v[132:133], s[14:15] op_sel_hi:[1,0]
	s_nop 0
	v_fma_f32 v132, -v186, v186, v187
	v_max_f32_e32 v132, 0, v132
	v_add_f32_e32 v132, 0x3727c5ac, v132
	v_mul_f32_e32 v133, 0x4f800000, v132
	v_cmp_gt_f32_e32 vcc, s44, v132
	s_nop 1
	v_cndmask_b32_e32 v136, v132, v133, vcc
	v_sqrt_f32_e32 v137, v136
	s_nop 0
	v_add_u32_e32 v132, -1, v137
	v_fma_f32 v133, -v132, v137, v136
	v_cmp_ge_f32_e64 s[0:1], 0, v133
	v_add_u32_e32 v139, 1, v137
	s_nop 0
	v_cndmask_b32_e64 v138, v137, v132, s[0:1]
	v_fma_f32 v137, -v139, v137, v136
	v_cmp_lt_f32_e64 s[0:1], 0, v137
	global_load_dwordx4 v[132:135], v[140:141], off offset:64 nt
	s_waitcnt vmcnt(1)
	v_pk_mul_f32 v[188:189], v[146:147], s[14:15] op_sel_hi:[1,0]
	v_cndmask_b32_e64 v137, v138, v139, s[0:1]
	v_mul_f32_e32 v138, 0x37800000, v137
	v_cndmask_b32_e32 v137, v137, v138, vcc
	v_cmp_class_f32_e32 vcc, v136, v182
	v_fma_f32 v146, -v188, v188, v189
	v_max_f32_e32 v146, 0, v146
	v_cndmask_b32_e32 v148, v137, v136, vcc
	v_div_scale_f32 v149, s[0:1], v148, v148, 1.0
	v_rcp_f32_e32 v150, v149
	global_load_dwordx4 v[128:131], v[140:141], off nt
	v_add_f32_e32 v146, 0x3727c5ac, v146
	v_mul_f32_e32 v147, 0x4f800000, v146
	v_cmp_gt_f32_e64 s[0:1], s44, v146
	v_fma_f32 v151, -v149, v150, 1.0
	v_fmac_f32_e32 v150, v151, v150
	v_cndmask_b32_e64 v153, v146, v147, s[0:1]
	v_sqrt_f32_e32 v146, v153
	v_div_scale_f32 v151, vcc, 1.0, v148, 1.0
	v_mul_f32_e32 v152, v151, v150
	v_fma_f32 v147, -v149, v152, v151
	v_fmac_f32_e32 v152, v147, v150
	v_add_u32_e32 v147, -1, v146
	v_fma_f32 v149, -v149, v152, v151
	v_fma_f32 v151, -v147, v146, v153
	v_add_u32_e32 v154, 1, v146
	global_load_dwordx4 v[136:139], v[140:141], off offset:576 nt
	s_nop 0
	global_load_dwordx4 v[140:143], v[140:141], off offset:512 nt
	v_cmp_ge_f32_e64 s[4:5], 0, v151
	v_fma_f32 v155, -v154, v146, v153
	v_div_fmas_f32 v149, v149, v150, v152
	v_cndmask_b32_e64 v151, v146, v147, s[4:5]
	v_cmp_lt_f32_e64 s[4:5], 0, v155
	global_load_dwordx4 v[144:147], v[156:157], off nt
	v_div_fixup_f32 v192, v149, v148, 1.0
	v_cndmask_b32_e64 v151, v151, v154, s[4:5]
	v_mul_f32_e32 v154, 0x37800000, v151
	v_cndmask_b32_e64 v151, v151, v154, s[0:1]
	v_cmp_class_f32_e64 s[0:1], v153, v182
	v_pk_mul_f32 v[196:197], v[124:125], v[192:193] op_sel_hi:[1,0]
	v_pk_mul_f32 v[198:199], v[126:127], v[192:193] op_sel_hi:[1,0]
	v_cndmask_b32_e64 v153, v151, v153, s[0:1]
	v_div_scale_f32 v154, s[0:1], v153, v153, 1.0
	v_rcp_f32_e32 v155, v154
	v_div_scale_f32 v152, vcc, 1.0, v153, 1.0
	v_fma_f32 v148, -v154, v155, 1.0
	v_fmac_f32_e32 v155, v148, v155
	global_load_dwordx4 v[148:151], v[156:157], off offset:64 nt
	v_mul_f32_e32 v158, v152, v155
	v_fma_f32 v159, -v154, v158, v152
	v_fmac_f32_e32 v158, v159, v155
	v_fma_f32 v152, -v154, v158, v152
	v_div_fmas_f32 v152, v152, v155, v158
	v_div_fixup_f32 v194, v152, v153, 1.0
	global_load_dwordx4 v[152:155], v[156:157], off offset:512 nt
	s_nop 0
	global_load_dwordx4 v[156:159], v[156:157], off offset:576 nt
	s_waitcnt vmcnt(6)
	v_sub_f32_e32 v129, v129, v186
	v_sub_f32_e32 v128, v128, v186
	v_sub_f32_e32 v131, v131, v186
	v_sub_f32_e32 v130, v130, v186
	v_pk_fma_f32 v[128:129], v[128:129], v[196:197], v[120:121]
	v_pk_fma_f32 v[130:131], v[130:131], v[198:199], v[122:123]
	v_pk_mul_f32 v[128:129], v[128:129], s[16:17] op_sel_hi:[1,0]
	v_pk_mul_f32 v[130:131], v[130:131], s[16:17] op_sel_hi:[1,0]
	v_pk_fma_f32 v[92:93], v[92:93], 0.5, v[128:129] op_sel_hi:[1,0,1]
	v_lshl_add_u64 v[128:129], s[38:39], 0, v[184:185]
	v_pk_fma_f32 v[94:95], v[94:95], 0.5, v[130:131] op_sel_hi:[1,0,1]
	v_lshl_add_u64 v[128:129], v[128:129], 0, v[168:169]
	ds_bpermute_b32 v246, v238, v92
	ds_bpermute_b32 v247, v238, v93
	ds_bpermute_b32 v248, v238, v94
	ds_bpermute_b32 v249, v238, v95
	v_lshl_add_u64 v[244:245], v[128:129], 0, v[240:241]
	s_waitcnt lgkmcnt(0)
;     __device__ __forceinline__ void operator()(const f32x4 (&acc)[2][2][4][2], const Unit& u, int wr, int wc, int fr, int fq) const {
;     ...
;                 for (int mm = 0; mm < 2; ++mm) {
;                     const int r = row0 + ai * HALF + (2 * m2 + mm) * 16;
;                     float ps = 0.f, pq = 0.f;
; #pragma unroll
;                     for (int bj = 0; bj < 2; ++bj)
; #pragma unroll
;                         for (int n = 0; n < 2; ++n) {
;                             const f32x4 x = (xv[mm][bj][n] - st[mm][0]) * (gg[bj][n] * st[mm][1]) + bb[bj][n];
;                             const f32x4 o = x * alpha + acc[ai][bj][2 * m2 + mm][n] * scale;
;                             const size_t off = (size_t)r * D + col0 + bj * HALF + n * 16;
;                             *(f32x4*)(Y + off) = o;
	global_store_dwordx4 v[244:245], v[246:249], off
	v_pk_mul_f32 v[130:131], v[116:117], v[192:193] op_sel_hi:[1,0]
	s_nop 0
	v_sub_f32_e32 v93, v133, v186
	v_sub_f32_e32 v92, v132, v186
	v_sub_f32_e32 v95, v135, v186
	v_sub_f32_e32 v94, v134, v186
	v_pk_mul_f32 v[132:133], v[118:119], v[192:193] op_sel_hi:[1,0]
	v_pk_fma_f32 v[92:93], v[92:93], v[130:131], v[112:113]
	v_pk_fma_f32 v[94:95], v[94:95], v[132:133], v[114:115]
	v_pk_mul_f32 v[92:93], v[92:93], s[16:17] op_sel_hi:[1,0]
	v_pk_mul_f32 v[94:95], v[94:95], s[16:17] op_sel_hi:[1,0]
	v_pk_fma_f32 v[88:89], v[88:89], 0.5, v[92:93] op_sel_hi:[1,0,1]
	v_pk_fma_f32 v[90:91], v[90:91], 0.5, v[94:95] op_sel_hi:[1,0,1]
	ds_bpermute_b32 v250, v238, v88
	ds_bpermute_b32 v251, v238, v89
	ds_bpermute_b32 v252, v238, v90
	ds_bpermute_b32 v253, v238, v91
	v_lshl_add_u64 v[244:245], v[128:129], 0, v[240:241]
	s_waitcnt lgkmcnt(0)
	global_store_dwordx4 v[244:245], v[250:253], off offset:64
	v_pk_mul_f32 v[92:93], v[108:109], v[192:193] op_sel_hi:[1,0]
	v_pk_mul_f32 v[94:95], v[110:111], v[192:193] op_sel_hi:[1,0]
	s_waitcnt vmcnt(6)
	v_sub_f32_e32 v89, v141, v186
	v_sub_f32_e32 v88, v140, v186
	v_sub_f32_e32 v91, v143, v186
	v_sub_f32_e32 v90, v142, v186
	v_pk_fma_f32 v[90:91], v[90:91], v[94:95], v[106:107]
	v_pk_fma_f32 v[88:89], v[88:89], v[92:93], v[104:105]
	v_pk_mul_f32 v[90:91], v[90:91], s[16:17] op_sel_hi:[1,0]
	v_pk_mul_f32 v[88:89], v[88:89], s[16:17] op_sel_hi:[1,0]
	v_pk_fma_f32 v[86:87], v[86:87], 0.5, v[90:91] op_sel_hi:[1,0,1]
	v_pk_fma_f32 v[84:85], v[84:85], 0.5, v[88:89] op_sel_hi:[1,0,1]
	ds_bpermute_b32 v246, v238, v84
	ds_bpermute_b32 v247, v238, v85
	ds_bpermute_b32 v248, v238, v86
	ds_bpermute_b32 v249, v238, v87
	v_lshl_add_u64 v[244:245], v[128:129], 0, v[240:241]
	s_waitcnt lgkmcnt(0)
	global_store_dwordx4 v[244:245], v[246:249], off offset:512
	v_pk_mul_f32 v[88:89], v[100:101], v[192:193] op_sel_hi:[1,0]
	v_pk_mul_f32 v[90:91], v[102:103], v[192:193] op_sel_hi:[1,0]
	v_sub_f32_e32 v85, v137, v186
	v_sub_f32_e32 v84, v136, v186
	v_sub_f32_e32 v87, v139, v186
	v_sub_f32_e32 v86, v138, v186
	v_pk_fma_f32 v[86:87], v[86:87], v[90:91], v[98:99]
	v_pk_fma_f32 v[84:85], v[84:85], v[88:89], v[96:97]
	v_pk_mul_f32 v[86:87], v[86:87], s[16:17] op_sel_hi:[1,0]
	v_pk_mul_f32 v[84:85], v[84:85], s[16:17] op_sel_hi:[1,0]
	v_pk_fma_f32 v[78:79], v[78:79], 0.5, v[86:87] op_sel_hi:[1,0,1]
	v_pk_fma_f32 v[76:77], v[76:77], 0.5, v[84:85] op_sel_hi:[1,0,1]
	ds_bpermute_b32 v250, v238, v76
	ds_bpermute_b32 v251, v238, v77
	ds_bpermute_b32 v252, v238, v78
	ds_bpermute_b32 v253, v238, v79
	v_lshl_add_u64 v[244:245], v[128:129], 0, v[240:241]
	s_waitcnt lgkmcnt(0)
	global_store_dwordx4 v[244:245], v[250:253], off offset:576
	v_pk_mul_f32 v[84:85], v[124:125], v[194:195] op_sel_hi:[1,0]
	v_pk_mul_f32 v[86:87], v[126:127], v[194:195] op_sel_hi:[1,0]
	s_waitcnt vmcnt(7)
	v_sub_f32_e32 v77, v145, v188
	v_sub_f32_e32 v76, v144, v188
	v_sub_f32_e32 v79, v147, v188
	v_sub_f32_e32 v78, v146, v188
	v_pk_fma_f32 v[76:77], v[76:77], v[84:85], v[120:121]
	v_pk_fma_f32 v[78:79], v[78:79], v[86:87], v[122:123]
	v_pk_mul_f32 v[76:77], v[76:77], s[16:17] op_sel_hi:[1,0]
	v_pk_mul_f32 v[78:79], v[78:79], s[16:17] op_sel_hi:[1,0]
	v_pk_fma_f32 v[76:77], v[80:81], 0.5, v[76:77] op_sel_hi:[1,0,1]
	v_lshl_add_u64 v[80:81], s[38:39], 0, v[190:191]
	v_pk_fma_f32 v[78:79], v[82:83], 0.5, v[78:79] op_sel_hi:[1,0,1]
	v_lshl_add_u64 v[80:81], v[80:81], 0, v[168:169]
	ds_bpermute_b32 v246, v238, v76
	ds_bpermute_b32 v247, v238, v77
	ds_bpermute_b32 v248, v238, v78
	ds_bpermute_b32 v249, v238, v79
	v_lshl_add_u64 v[244:245], v[80:81], 0, v[240:241]
	s_waitcnt lgkmcnt(0)
	global_store_dwordx4 v[244:245], v[246:249], off
	v_pk_mul_f32 v[82:83], v[116:117], v[194:195] op_sel_hi:[1,0]
	v_pk_mul_f32 v[84:85], v[118:119], v[194:195] op_sel_hi:[1,0]
	s_waitcnt vmcnt(7)
	v_sub_f32_e32 v77, v149, v188
	v_sub_f32_e32 v76, v148, v188
	v_sub_f32_e32 v79, v151, v188
	v_sub_f32_e32 v78, v150, v188
	v_pk_fma_f32 v[78:79], v[78:79], v[84:85], v[114:115]
	v_pk_fma_f32 v[76:77], v[76:77], v[82:83], v[112:113]
	v_pk_mul_f32 v[78:79], v[78:79], s[16:17] op_sel_hi:[1,0]
	v_pk_mul_f32 v[76:77], v[76:77], s[16:17] op_sel_hi:[1,0]
	v_pk_fma_f32 v[74:75], v[74:75], 0.5, v[78:79] op_sel_hi:[1,0,1]
	v_pk_fma_f32 v[72:73], v[72:73], 0.5, v[76:77] op_sel_hi:[1,0,1]
	ds_bpermute_b32 v250, v238, v72
	ds_bpermute_b32 v251, v238, v73
	ds_bpermute_b32 v252, v238, v74
	ds_bpermute_b32 v253, v238, v75
	v_lshl_add_u64 v[244:245], v[80:81], 0, v[240:241]
	s_waitcnt lgkmcnt(0)
	global_store_dwordx4 v[244:245], v[250:253], off offset:64
	v_pk_mul_f32 v[76:77], v[108:109], v[194:195] op_sel_hi:[1,0]
	v_pk_mul_f32 v[78:79], v[110:111], v[194:195] op_sel_hi:[1,0]
	s_waitcnt vmcnt(7)
	v_sub_f32_e32 v73, v153, v188
	v_sub_f32_e32 v72, v152, v188
	v_sub_f32_e32 v75, v155, v188
	v_sub_f32_e32 v74, v154, v188
	v_pk_fma_f32 v[74:75], v[74:75], v[78:79], v[106:107]
	v_pk_fma_f32 v[72:73], v[72:73], v[76:77], v[104:105]
	v_pk_mul_f32 v[74:75], v[74:75], s[16:17] op_sel_hi:[1,0]
	v_pk_mul_f32 v[72:73], v[72:73], s[16:17] op_sel_hi:[1,0]
	v_pk_fma_f32 v[70:71], v[70:71], 0.5, v[74:75] op_sel_hi:[1,0,1]
	v_pk_fma_f32 v[68:69], v[68:69], 0.5, v[72:73] op_sel_hi:[1,0,1]
	ds_bpermute_b32 v246, v238, v68
	ds_bpermute_b32 v247, v238, v69
	ds_bpermute_b32 v248, v238, v70
	ds_bpermute_b32 v249, v238, v71
	v_lshl_add_u64 v[244:245], v[80:81], 0, v[240:241]
	s_waitcnt lgkmcnt(0)
	global_store_dwordx4 v[244:245], v[246:249], off offset:512
	v_pk_mul_f32 v[72:73], v[100:101], v[194:195] op_sel_hi:[1,0]
	v_pk_mul_f32 v[74:75], v[102:103], v[194:195] op_sel_hi:[1,0]
	s_waitcnt vmcnt(7)
; __device__ __forceinline__ f32x2 ln_stats(f32x2 sm) { const float mu = sm[0] * (1.f / D); const float var = fmaxf(sm[1] * (1.f / D) - mu * mu, 0.f); return (f32x2){mu, 1.0f / sqrtf(var + LN_EPS)}; }
;     __device__ __forceinline__ void operator()(const f32x4 (&acc)[2][2][4][2], const Unit& u, int wr, int wc, int fr, int fq) const {
;     ...
;                 f32x4 xv[2][2][2]; f32x2 st[2];
; #pragma unroll
;                 for (int mm = 0; mm < 2; ++mm) {
;                     const int r = row0 + ai * HALF + (2 * m2 + mm) * 16;
;                     st[mm] = (f32x2){0.f, 1.f};
;                     if (rin) st[mm] = ln_stats(*(const f32x2*)(rin + 2 * (size_t)r));
; #pragma unroll
;                     for (int bj = 0; bj < 2; ++bj)
; #pragma unroll
;                         for (int n = 0; n < 2; ++n) { const f32x4* rp = (const f32x4*)(res + (size_t)r * D + col0 + bj * HALF + n * 16); xv[mm][bj][n] = stream ? __builtin_nontemporal_load(rp) : *rp; }
;                 }
; #pragma unroll
;                 for (int mm = 0; mm < 2; ++mm) {
;                     const int r = row0 + ai * HALF + (2 * m2 + mm) * 16;
;                     float ps = 0.f, pq = 0.f;
; #pragma unroll
;                     for (int bj = 0; bj < 2; ++bj)
; #pragma unroll
;                         for (int n = 0; n < 2; ++n) {
;                             const f32x4 x = (xv[mm][bj][n] - st[mm][0]) * (gg[bj][n] * st[mm][1]) + bb[bj][n];
;                             const f32x4 o = x * alpha + acc[ai][bj][2 * m2 + mm][n] * scale;
;                             const size_t off = (size_t)r * D + col0 + bj * HALF + n * 16;
;                             *(f32x4*)(Y + off) = o;
	v_sub_f32_e32 v69, v157, v188
	v_sub_f32_e32 v68, v156, v188
	v_sub_f32_e32 v71, v159, v188
	v_sub_f32_e32 v70, v158, v188
	v_pk_fma_f32 v[70:71], v[70:71], v[74:75], v[98:99]
	v_pk_fma_f32 v[68:69], v[68:69], v[72:73], v[96:97]
	v_pk_mul_f32 v[70:71], v[70:71], s[16:17] op_sel_hi:[1,0]
	v_pk_mul_f32 v[68:69], v[68:69], s[16:17] op_sel_hi:[1,0]
	v_pk_fma_f32 v[66:67], v[66:67], 0.5, v[70:71] op_sel_hi:[1,0,1]
	v_pk_fma_f32 v[64:65], v[64:65], 0.5, v[68:69] op_sel_hi:[1,0,1]
	ds_bpermute_b32 v250, v238, v64
	ds_bpermute_b32 v251, v238, v65
	ds_bpermute_b32 v252, v238, v66
	ds_bpermute_b32 v253, v238, v67
	v_lshl_add_u64 v[244:245], v[80:81], 0, v[240:241]
	s_waitcnt lgkmcnt(0)
	global_store_dwordx4 v[244:245], v[250:253], off offset:576
	v_add_u32_e32 v80, 0x90, v172
	v_ashrrev_i32_e32 v81, 31, v80
	v_add_u32_e32 v64, 0x80, v172
	v_ashrrev_i32_e32 v65, 31, v64
	v_lshl_add_u64 v[66:67], v[64:65], 3, s[8:9]
	global_load_dwordx2 v[68:69], v[66:67], off
	v_lshl_add_u64 v[66:67], v[80:81], 3, s[8:9]
	global_load_dwordx2 v[82:83], v[66:67], off
	v_lshlrev_b64 v[128:129], 13, v[64:65]
	v_lshl_add_u64 v[76:77], v[170:171], 0, v[128:129]
	v_lshlrev_b64 v[134:135], 13, v[80:81]
	v_lshl_add_u64 v[92:93], v[170:171], 0, v[134:135]
	s_waitcnt vmcnt(1)
	v_pk_mul_f32 v[130:131], v[68:69], s[14:15] op_sel_hi:[1,0]
	s_nop 0
	v_fma_f32 v68, -v130, v130, v131
	v_max_f32_e32 v68, 0, v68
	v_add_f32_e32 v68, 0x3727c5ac, v68
	v_mul_f32_e32 v69, 0x4f800000, v68
	v_cmp_gt_f32_e32 vcc, s44, v68
	s_nop 1
	v_cndmask_b32_e32 v72, v68, v69, vcc
	v_sqrt_f32_e32 v73, v72
	s_nop 0
	v_add_u32_e32 v68, -1, v73
	v_fma_f32 v69, -v68, v73, v72
	v_cmp_ge_f32_e64 s[0:1], 0, v69
	v_add_u32_e32 v75, 1, v73
	s_nop 0
	v_cndmask_b32_e64 v74, v73, v68, s[0:1]
	v_fma_f32 v73, -v75, v73, v72
	v_cmp_lt_f32_e64 s[0:1], 0, v73
	global_load_dwordx4 v[68:71], v[76:77], off offset:64 nt
	s_waitcnt vmcnt(1)
	v_pk_mul_f32 v[132:133], v[82:83], s[14:15] op_sel_hi:[1,0]
	v_cndmask_b32_e64 v73, v74, v75, s[0:1]
	v_mul_f32_e32 v74, 0x37800000, v73
	v_cndmask_b32_e32 v73, v73, v74, vcc
	v_cmp_class_f32_e32 vcc, v72, v182
	v_fma_f32 v82, -v132, v132, v133
	v_max_f32_e32 v82, 0, v82
	v_cndmask_b32_e32 v84, v73, v72, vcc
	v_div_scale_f32 v85, s[0:1], v84, v84, 1.0
	v_rcp_f32_e32 v86, v85
	global_load_dwordx4 v[64:67], v[76:77], off nt
	v_add_f32_e32 v82, 0x3727c5ac, v82
	v_mul_f32_e32 v83, 0x4f800000, v82
	v_cmp_gt_f32_e64 s[0:1], s44, v82
	v_fma_f32 v87, -v85, v86, 1.0
	v_fmac_f32_e32 v86, v87, v86
	v_cndmask_b32_e64 v89, v82, v83, s[0:1]
	v_sqrt_f32_e32 v82, v89
	v_div_scale_f32 v87, vcc, 1.0, v84, 1.0
	v_mul_f32_e32 v88, v87, v86
	v_fma_f32 v83, -v85, v88, v87
	v_fmac_f32_e32 v88, v83, v86
	v_add_u32_e32 v83, -1, v82
	v_fma_f32 v85, -v85, v88, v87
	v_fma_f32 v87, -v83, v82, v89
	v_add_u32_e32 v90, 1, v82
	global_load_dwordx4 v[72:75], v[76:77], off offset:576 nt
	s_nop 0
	global_load_dwordx4 v[76:79], v[76:77], off offset:512 nt
	v_cmp_ge_f32_e64 s[4:5], 0, v87
	v_fma_f32 v91, -v90, v82, v89
	v_div_fmas_f32 v85, v85, v86, v88
	v_cndmask_b32_e64 v87, v82, v83, s[4:5]
	v_cmp_lt_f32_e64 s[4:5], 0, v91
	global_load_dwordx4 v[80:83], v[92:93], off nt
	v_div_fixup_f32 v136, v85, v84, 1.0
	v_cndmask_b32_e64 v87, v87, v90, s[4:5]
	v_mul_f32_e32 v90, 0x37800000, v87
	v_cndmask_b32_e64 v87, v87, v90, s[0:1]
	v_cmp_class_f32_e64 s[0:1], v89, v182
	v_pk_mul_f32 v[140:141], v[124:125], v[136:137] op_sel_hi:[1,0]
	v_pk_mul_f32 v[142:143], v[126:127], v[136:137] op_sel_hi:[1,0]
	v_cndmask_b32_e64 v89, v87, v89, s[0:1]
	v_div_scale_f32 v90, s[0:1], v89, v89, 1.0
	v_rcp_f32_e32 v91, v90
	v_div_scale_f32 v88, vcc, 1.0, v89, 1.0
	v_fma_f32 v84, -v90, v91, 1.0
	v_fmac_f32_e32 v91, v84, v91
	global_load_dwordx4 v[84:87], v[92:93], off offset:64 nt
	v_mul_f32_e32 v94, v88, v91
	v_fma_f32 v95, -v90, v94, v88
	v_fmac_f32_e32 v94, v95, v91
	v_fma_f32 v88, -v90, v94, v88
	v_div_fmas_f32 v88, v88, v91, v94
	v_div_fixup_f32 v138, v88, v89, 1.0
	global_load_dwordx4 v[88:91], v[92:93], off offset:512 nt
	s_nop 0
	global_load_dwordx4 v[92:95], v[92:93], off offset:576 nt
	s_waitcnt vmcnt(6)
	v_sub_f32_e32 v65, v65, v130
	v_sub_f32_e32 v64, v64, v130
	v_sub_f32_e32 v67, v67, v130
	v_sub_f32_e32 v66, v66, v130
	v_pk_fma_f32 v[64:65], v[64:65], v[140:141], v[120:121]
	v_pk_fma_f32 v[66:67], v[66:67], v[142:143], v[122:123]
	v_pk_mul_f32 v[64:65], v[64:65], s[16:17] op_sel_hi:[1,0]
	v_pk_mul_f32 v[66:67], v[66:67], s[16:17] op_sel_hi:[1,0]
	v_pk_fma_f32 v[60:61], v[60:61], 0.5, v[64:65] op_sel_hi:[1,0,1]
	v_lshl_add_u64 v[64:65], s[38:39], 0, v[128:129]
	v_pk_fma_f32 v[62:63], v[62:63], 0.5, v[66:67] op_sel_hi:[1,0,1]
	v_lshl_add_u64 v[64:65], v[64:65], 0, v[168:169]
	ds_bpermute_b32 v246, v238, v60
	ds_bpermute_b32 v247, v238, v61
	ds_bpermute_b32 v248, v238, v62
	ds_bpermute_b32 v249, v238, v63
	v_lshl_add_u64 v[244:245], v[64:65], 0, v[240:241]
	s_waitcnt lgkmcnt(0)
	global_store_dwordx4 v[244:245], v[246:249], off
	v_pk_mul_f32 v[66:67], v[116:117], v[136:137] op_sel_hi:[1,0]
	s_nop 0
	v_sub_f32_e32 v61, v69, v130
	v_sub_f32_e32 v60, v68, v130
	v_sub_f32_e32 v63, v71, v130
	v_sub_f32_e32 v62, v70, v130
	v_pk_mul_f32 v[68:69], v[118:119], v[136:137] op_sel_hi:[1,0]
	v_pk_fma_f32 v[60:61], v[60:61], v[66:67], v[112:113]
	v_pk_fma_f32 v[62:63], v[62:63], v[68:69], v[114:115]
	v_pk_mul_f32 v[60:61], v[60:61], s[16:17] op_sel_hi:[1,0]
	v_pk_mul_f32 v[62:63], v[62:63], s[16:17] op_sel_hi:[1,0]
	v_pk_fma_f32 v[56:57], v[56:57], 0.5, v[60:61] op_sel_hi:[1,0,1]
	v_pk_fma_f32 v[58:59], v[58:59], 0.5, v[62:63] op_sel_hi:[1,0,1]
	ds_bpermute_b32 v250, v238, v56
	ds_bpermute_b32 v251, v238, v57
	ds_bpermute_b32 v252, v238, v58
	ds_bpermute_b32 v253, v238, v59
	v_lshl_add_u64 v[244:245], v[64:65], 0, v[240:241]
	s_waitcnt lgkmcnt(0)
;     __device__ __forceinline__ void operator()(const f32x4 (&acc)[2][2][4][2], const Unit& u, int wr, int wc, int fr, int fq) const {
;     ...
;                 for (int mm = 0; mm < 2; ++mm) {
;                     const int r = row0 + ai * HALF + (2 * m2 + mm) * 16;
;                     float ps = 0.f, pq = 0.f;
; #pragma unroll
;                     for (int bj = 0; bj < 2; ++bj)
; #pragma unroll
;                         for (int n = 0; n < 2; ++n) {
;                             const f32x4 x = (xv[mm][bj][n] - st[mm][0]) * (gg[bj][n] * st[mm][1]) + bb[bj][n];
;                             const f32x4 o = x * alpha + acc[ai][bj][2 * m2 + mm][n] * scale;
;                             const size_t off = (size_t)r * D + col0 + bj * HALF + n * 16;
;                             *(f32x4*)(Y + off) = o;
	global_store_dwordx4 v[244:245], v[250:253], off offset:64
	v_pk_mul_f32 v[60:61], v[108:109], v[136:137] op_sel_hi:[1,0]
	v_pk_mul_f32 v[62:63], v[110:111], v[136:137] op_sel_hi:[1,0]
	s_waitcnt vmcnt(6)
	v_sub_f32_e32 v57, v77, v130
	v_sub_f32_e32 v56, v76, v130
	v_sub_f32_e32 v59, v79, v130
	v_sub_f32_e32 v58, v78, v130
	v_pk_fma_f32 v[58:59], v[58:59], v[62:63], v[106:107]
	v_pk_fma_f32 v[56:57], v[56:57], v[60:61], v[104:105]
	v_pk_mul_f32 v[58:59], v[58:59], s[16:17] op_sel_hi:[1,0]
	v_pk_mul_f32 v[56:57], v[56:57], s[16:17] op_sel_hi:[1,0]
	v_pk_fma_f32 v[54:55], v[54:55], 0.5, v[58:59] op_sel_hi:[1,0,1]
	v_pk_fma_f32 v[52:53], v[52:53], 0.5, v[56:57] op_sel_hi:[1,0,1]
	ds_bpermute_b32 v246, v238, v52
	ds_bpermute_b32 v247, v238, v53
	ds_bpermute_b32 v248, v238, v54
	ds_bpermute_b32 v249, v238, v55
	v_lshl_add_u64 v[244:245], v[64:65], 0, v[240:241]
	s_waitcnt lgkmcnt(0)
	global_store_dwordx4 v[244:245], v[246:249], off offset:512
	v_pk_mul_f32 v[56:57], v[100:101], v[136:137] op_sel_hi:[1,0]
	v_pk_mul_f32 v[58:59], v[102:103], v[136:137] op_sel_hi:[1,0]
	v_sub_f32_e32 v53, v73, v130
	v_sub_f32_e32 v52, v72, v130
	v_sub_f32_e32 v55, v75, v130
	v_sub_f32_e32 v54, v74, v130
	v_pk_fma_f32 v[54:55], v[54:55], v[58:59], v[98:99]
	v_pk_fma_f32 v[52:53], v[52:53], v[56:57], v[96:97]
	v_pk_mul_f32 v[54:55], v[54:55], s[16:17] op_sel_hi:[1,0]
	v_pk_mul_f32 v[52:53], v[52:53], s[16:17] op_sel_hi:[1,0]
	v_pk_fma_f32 v[46:47], v[46:47], 0.5, v[54:55] op_sel_hi:[1,0,1]
	v_pk_fma_f32 v[44:45], v[44:45], 0.5, v[52:53] op_sel_hi:[1,0,1]
	ds_bpermute_b32 v250, v238, v44
	ds_bpermute_b32 v251, v238, v45
	ds_bpermute_b32 v252, v238, v46
	ds_bpermute_b32 v253, v238, v47
	v_lshl_add_u64 v[244:245], v[64:65], 0, v[240:241]
	s_waitcnt lgkmcnt(0)
	global_store_dwordx4 v[244:245], v[250:253], off offset:576
	v_pk_mul_f32 v[52:53], v[124:125], v[138:139] op_sel_hi:[1,0]
	v_pk_mul_f32 v[54:55], v[126:127], v[138:139] op_sel_hi:[1,0]
	s_waitcnt vmcnt(7)
	v_sub_f32_e32 v45, v81, v132
	v_sub_f32_e32 v44, v80, v132
	v_sub_f32_e32 v47, v83, v132
	v_sub_f32_e32 v46, v82, v132
	v_pk_fma_f32 v[44:45], v[44:45], v[52:53], v[120:121]
	v_pk_fma_f32 v[46:47], v[46:47], v[54:55], v[122:123]
	v_pk_mul_f32 v[44:45], v[44:45], s[16:17] op_sel_hi:[1,0]
	v_pk_mul_f32 v[46:47], v[46:47], s[16:17] op_sel_hi:[1,0]
	v_pk_fma_f32 v[44:45], v[48:49], 0.5, v[44:45] op_sel_hi:[1,0,1]
	v_lshl_add_u64 v[48:49], s[38:39], 0, v[134:135]
	v_pk_fma_f32 v[46:47], v[50:51], 0.5, v[46:47] op_sel_hi:[1,0,1]
	v_lshl_add_u64 v[48:49], v[48:49], 0, v[168:169]
	ds_bpermute_b32 v246, v238, v44
	ds_bpermute_b32 v247, v238, v45
	ds_bpermute_b32 v248, v238, v46
	ds_bpermute_b32 v249, v238, v47
	v_lshl_add_u64 v[244:245], v[48:49], 0, v[240:241]
	s_waitcnt lgkmcnt(0)
	global_store_dwordx4 v[244:245], v[246:249], off
	v_pk_mul_f32 v[50:51], v[116:117], v[138:139] op_sel_hi:[1,0]
	v_pk_mul_f32 v[52:53], v[118:119], v[138:139] op_sel_hi:[1,0]
	s_waitcnt vmcnt(7)
	v_sub_f32_e32 v45, v85, v132
	v_sub_f32_e32 v44, v84, v132
	v_sub_f32_e32 v47, v87, v132
	v_sub_f32_e32 v46, v86, v132
	v_pk_fma_f32 v[46:47], v[46:47], v[52:53], v[114:115]
	v_pk_fma_f32 v[44:45], v[44:45], v[50:51], v[112:113]
	v_pk_mul_f32 v[46:47], v[46:47], s[16:17] op_sel_hi:[1,0]
	v_pk_mul_f32 v[44:45], v[44:45], s[16:17] op_sel_hi:[1,0]
	v_pk_fma_f32 v[42:43], v[42:43], 0.5, v[46:47] op_sel_hi:[1,0,1]
	v_pk_fma_f32 v[40:41], v[40:41], 0.5, v[44:45] op_sel_hi:[1,0,1]
	ds_bpermute_b32 v250, v238, v40
	ds_bpermute_b32 v251, v238, v41
	ds_bpermute_b32 v252, v238, v42
	ds_bpermute_b32 v253, v238, v43
	v_lshl_add_u64 v[244:245], v[48:49], 0, v[240:241]
	s_waitcnt lgkmcnt(0)
	global_store_dwordx4 v[244:245], v[250:253], off offset:64
	v_pk_mul_f32 v[44:45], v[108:109], v[138:139] op_sel_hi:[1,0]
	v_pk_mul_f32 v[46:47], v[110:111], v[138:139] op_sel_hi:[1,0]
	s_waitcnt vmcnt(7)
	v_sub_f32_e32 v41, v89, v132
	v_sub_f32_e32 v40, v88, v132
	v_sub_f32_e32 v43, v91, v132
	v_sub_f32_e32 v42, v90, v132
	v_pk_fma_f32 v[42:43], v[42:43], v[46:47], v[106:107]
	v_pk_fma_f32 v[40:41], v[40:41], v[44:45], v[104:105]
	v_pk_mul_f32 v[42:43], v[42:43], s[16:17] op_sel_hi:[1,0]
	v_pk_mul_f32 v[40:41], v[40:41], s[16:17] op_sel_hi:[1,0]
	v_pk_fma_f32 v[38:39], v[38:39], 0.5, v[42:43] op_sel_hi:[1,0,1]
	v_pk_fma_f32 v[36:37], v[36:37], 0.5, v[40:41] op_sel_hi:[1,0,1]
	ds_bpermute_b32 v246, v238, v36
	ds_bpermute_b32 v247, v238, v37
	ds_bpermute_b32 v248, v238, v38
	ds_bpermute_b32 v249, v238, v39
	v_lshl_add_u64 v[244:245], v[48:49], 0, v[240:241]
	s_waitcnt lgkmcnt(0)
	global_store_dwordx4 v[244:245], v[246:249], off offset:512
	v_pk_mul_f32 v[40:41], v[100:101], v[138:139] op_sel_hi:[1,0]
	v_pk_mul_f32 v[42:43], v[102:103], v[138:139] op_sel_hi:[1,0]
	s_waitcnt vmcnt(7)
	v_sub_f32_e32 v37, v93, v132
	v_sub_f32_e32 v36, v92, v132
	v_sub_f32_e32 v39, v95, v132
	v_sub_f32_e32 v38, v94, v132
	v_pk_fma_f32 v[38:39], v[38:39], v[42:43], v[98:99]
	v_pk_fma_f32 v[36:37], v[36:37], v[40:41], v[96:97]
	v_pk_mul_f32 v[38:39], v[38:39], s[16:17] op_sel_hi:[1,0]
	v_pk_mul_f32 v[36:37], v[36:37], s[16:17] op_sel_hi:[1,0]
	v_pk_fma_f32 v[34:35], v[34:35], 0.5, v[38:39] op_sel_hi:[1,0,1]
	v_pk_fma_f32 v[32:33], v[32:33], 0.5, v[36:37] op_sel_hi:[1,0,1]
	ds_bpermute_b32 v250, v238, v32
	ds_bpermute_b32 v251, v238, v33
	ds_bpermute_b32 v252, v238, v34
	ds_bpermute_b32 v253, v238, v35
	v_lshl_add_u64 v[244:245], v[48:49], 0, v[240:241]
	s_waitcnt lgkmcnt(0)
; __device__ __forceinline__ f32x2 ln_stats(f32x2 sm) { const float mu = sm[0] * (1.f / D); const float var = fmaxf(sm[1] * (1.f / D) - mu * mu, 0.f); return (f32x2){mu, 1.0f / sqrtf(var + LN_EPS)}; }
;     __device__ __forceinline__ void operator()(const f32x4 (&acc)[2][2][4][2], const Unit& u, int wr, int wc, int fr, int fq) const {
;     ...
;                 f32x4 xv[2][2][2]; f32x2 st[2];
; #pragma unroll
;                 for (int mm = 0; mm < 2; ++mm) {
;                     const int r = row0 + ai * HALF + (2 * m2 + mm) * 16;
;                     st[mm] = (f32x2){0.f, 1.f};
;                     if (rin) st[mm] = ln_stats(*(const f32x2*)(rin + 2 * (size_t)r));
; #pragma unroll
;                     for (int bj = 0; bj < 2; ++bj)
; #pragma unroll
;                         for (int n = 0; n < 2; ++n) { const f32x4* rp = (const f32x4*)(res + (size_t)r * D + col0 + bj * HALF + n * 16); xv[mm][bj][n] = stream ? __builtin_nontemporal_load(rp) : *rp; }
;                 }
; #pragma unroll
;                 for (int mm = 0; mm < 2; ++mm) {
;                     const int r = row0 + ai * HALF + (2 * m2 + mm) * 16;
;                     float ps = 0.f, pq = 0.f;
; #pragma unroll
;                     for (int bj = 0; bj < 2; ++bj)
; #pragma unroll
;                         for (int n = 0; n < 2; ++n) {
;                             const f32x4 x = (xv[mm][bj][n] - st[mm][0]) * (gg[bj][n] * st[mm][1]) + bb[bj][n];
;                             const f32x4 o = x * alpha + acc[ai][bj][2 * m2 + mm][n] * scale;
;                             const size_t off = (size_t)r * D + col0 + bj * HALF + n * 16;
;                             *(f32x4*)(Y + off) = o;
	global_store_dwordx4 v[244:245], v[250:253], off offset:576
	v_add_u32_e32 v48, 0xb0, v172
	v_ashrrev_i32_e32 v49, 31, v48
	v_add_u32_e32 v32, 0xa0, v172
	v_ashrrev_i32_e32 v33, 31, v32
	v_lshl_add_u64 v[34:35], v[32:33], 3, s[8:9]
	global_load_dwordx2 v[36:37], v[34:35], off
	v_lshl_add_u64 v[34:35], v[48:49], 3, s[8:9]
	global_load_dwordx2 v[50:51], v[34:35], off
	v_lshlrev_b64 v[64:65], 13, v[32:33]
	v_lshl_add_u64 v[44:45], v[170:171], 0, v[64:65]
	v_lshlrev_b64 v[70:71], 13, v[48:49]
	v_lshl_add_u64 v[60:61], v[170:171], 0, v[70:71]
	s_waitcnt vmcnt(1)
	v_pk_mul_f32 v[66:67], v[36:37], s[14:15] op_sel_hi:[1,0]
	s_nop 0
	v_fma_f32 v36, -v66, v66, v67
	v_max_f32_e32 v36, 0, v36
	v_add_f32_e32 v36, 0x3727c5ac, v36
	v_mul_f32_e32 v37, 0x4f800000, v36
	v_cmp_gt_f32_e32 vcc, s44, v36
	s_nop 1
	v_cndmask_b32_e32 v40, v36, v37, vcc
	v_sqrt_f32_e32 v41, v40
	s_nop 0
	v_add_u32_e32 v36, -1, v41
	v_fma_f32 v37, -v36, v41, v40
	v_cmp_ge_f32_e64 s[0:1], 0, v37
	v_add_u32_e32 v43, 1, v41
	s_nop 0
	v_cndmask_b32_e64 v42, v41, v36, s[0:1]
	v_fma_f32 v41, -v43, v41, v40
	v_cmp_lt_f32_e64 s[0:1], 0, v41
	global_load_dwordx4 v[36:39], v[44:45], off offset:64 nt
	s_waitcnt vmcnt(1)
	v_pk_mul_f32 v[68:69], v[50:51], s[14:15] op_sel_hi:[1,0]
	v_cndmask_b32_e64 v41, v42, v43, s[0:1]
	v_mul_f32_e32 v42, 0x37800000, v41
	v_cndmask_b32_e32 v41, v41, v42, vcc
	v_cmp_class_f32_e32 vcc, v40, v182
	v_fma_f32 v50, -v68, v68, v69
	v_max_f32_e32 v50, 0, v50
	v_cndmask_b32_e32 v52, v41, v40, vcc
	v_div_scale_f32 v53, s[0:1], v52, v52, 1.0
	v_rcp_f32_e32 v54, v53
	global_load_dwordx4 v[32:35], v[44:45], off nt
	v_add_f32_e32 v50, 0x3727c5ac, v50
	v_mul_f32_e32 v51, 0x4f800000, v50
	v_cmp_gt_f32_e64 s[0:1], s44, v50
	v_fma_f32 v55, -v53, v54, 1.0
	v_fmac_f32_e32 v54, v55, v54
	v_cndmask_b32_e64 v57, v50, v51, s[0:1]
	v_sqrt_f32_e32 v50, v57
	v_div_scale_f32 v55, vcc, 1.0, v52, 1.0
	v_mul_f32_e32 v56, v55, v54
	v_fma_f32 v51, -v53, v56, v55
	v_fmac_f32_e32 v56, v51, v54
	v_add_u32_e32 v51, -1, v50
	v_fma_f32 v53, -v53, v56, v55
	v_fma_f32 v55, -v51, v50, v57
	v_add_u32_e32 v58, 1, v50
	global_load_dwordx4 v[40:43], v[44:45], off offset:576 nt
	s_nop 0
	global_load_dwordx4 v[44:47], v[44:45], off offset:512 nt
	v_cmp_ge_f32_e64 s[4:5], 0, v55
	v_fma_f32 v59, -v58, v50, v57
	v_div_fmas_f32 v53, v53, v54, v56
	v_cndmask_b32_e64 v55, v50, v51, s[4:5]
	v_cmp_lt_f32_e64 s[4:5], 0, v59
	global_load_dwordx4 v[48:51], v[60:61], off nt
	v_div_fixup_f32 v72, v53, v52, 1.0
	v_cndmask_b32_e64 v55, v55, v58, s[4:5]
	v_mul_f32_e32 v58, 0x37800000, v55
	v_cndmask_b32_e64 v55, v55, v58, s[0:1]
	v_cmp_class_f32_e64 s[0:1], v57, v182
	v_pk_mul_f32 v[76:77], v[124:125], v[72:73] op_sel_hi:[1,0]
	v_pk_mul_f32 v[78:79], v[126:127], v[72:73] op_sel_hi:[1,0]
	v_cndmask_b32_e64 v57, v55, v57, s[0:1]
	v_div_scale_f32 v58, s[0:1], v57, v57, 1.0
	v_rcp_f32_e32 v59, v58
	v_div_scale_f32 v56, vcc, 1.0, v57, 1.0
	s_mov_b64 s[0:1], -1
	v_fma_f32 v52, -v58, v59, 1.0
	v_fmac_f32_e32 v59, v52, v59
	global_load_dwordx4 v[52:55], v[60:61], off offset:64 nt
	v_mul_f32_e32 v62, v56, v59
	v_fma_f32 v63, -v58, v62, v56
	v_fmac_f32_e32 v62, v63, v59
	v_fma_f32 v56, -v58, v62, v56
	v_div_fmas_f32 v56, v56, v59, v62
	v_div_fixup_f32 v74, v56, v57, 1.0
	global_load_dwordx4 v[56:59], v[60:61], off offset:512 nt
	s_nop 0
	global_load_dwordx4 v[60:63], v[60:61], off offset:576 nt
	s_andn2_b64 vcc, exec, s[18:19]
	s_waitcnt vmcnt(6)
	v_sub_f32_e32 v33, v33, v66
	v_sub_f32_e32 v32, v32, v66
	v_sub_f32_e32 v35, v35, v66
	v_sub_f32_e32 v34, v34, v66
	v_pk_fma_f32 v[32:33], v[32:33], v[76:77], v[120:121]
	v_pk_fma_f32 v[34:35], v[34:35], v[78:79], v[122:123]
	v_pk_mul_f32 v[32:33], v[32:33], s[16:17] op_sel_hi:[1,0]
	v_pk_mul_f32 v[34:35], v[34:35], s[16:17] op_sel_hi:[1,0]
	v_pk_fma_f32 v[28:29], v[28:29], 0.5, v[32:33] op_sel_hi:[1,0,1]
	v_lshl_add_u64 v[32:33], s[38:39], 0, v[64:65]
	v_pk_fma_f32 v[30:31], v[30:31], 0.5, v[34:35] op_sel_hi:[1,0,1]
	v_lshl_add_u64 v[32:33], v[32:33], 0, v[168:169]
	ds_bpermute_b32 v246, v238, v28
	ds_bpermute_b32 v247, v238, v29
	ds_bpermute_b32 v248, v238, v30
	ds_bpermute_b32 v249, v238, v31
	v_lshl_add_u64 v[244:245], v[32:33], 0, v[240:241]
	s_waitcnt lgkmcnt(0)
	global_store_dwordx4 v[244:245], v[246:249], off
	v_pk_mul_f32 v[34:35], v[116:117], v[72:73] op_sel_hi:[1,0]
	s_nop 0
	v_sub_f32_e32 v29, v37, v66
	v_sub_f32_e32 v28, v36, v66
	v_sub_f32_e32 v31, v39, v66
	v_sub_f32_e32 v30, v38, v66
	v_pk_mul_f32 v[36:37], v[118:119], v[72:73] op_sel_hi:[1,0]
	v_pk_fma_f32 v[28:29], v[28:29], v[34:35], v[112:113]
	v_pk_fma_f32 v[30:31], v[30:31], v[36:37], v[114:115]
	v_pk_mul_f32 v[28:29], v[28:29], s[16:17] op_sel_hi:[1,0]
	v_pk_mul_f32 v[30:31], v[30:31], s[16:17] op_sel_hi:[1,0]
	v_pk_fma_f32 v[24:25], v[24:25], 0.5, v[28:29] op_sel_hi:[1,0,1]
	v_pk_fma_f32 v[26:27], v[26:27], 0.5, v[30:31] op_sel_hi:[1,0,1]
	ds_bpermute_b32 v250, v238, v24
	ds_bpermute_b32 v251, v238, v25
	ds_bpermute_b32 v252, v238, v26
	ds_bpermute_b32 v253, v238, v27
	v_lshl_add_u64 v[244:245], v[32:33], 0, v[240:241]
	s_waitcnt lgkmcnt(0)
	global_store_dwordx4 v[244:245], v[250:253], off offset:64
	v_pk_mul_f32 v[28:29], v[108:109], v[72:73] op_sel_hi:[1,0]
	v_pk_mul_f32 v[30:31], v[110:111], v[72:73] op_sel_hi:[1,0]
	s_waitcnt vmcnt(6)
; #define PG8_BAR __builtin_amdgcn_s_barrier()
; template <class Sched, class Epi, bool ALIGN_EPI, bool SP2>
; __device__ __forceinline__ void gemm_phase(LAS unsigned char* lds, const int K, const int lda, const int ldb, const Sched& S, const Epi& E) {
;     ...
;         if constexpr (ALIGN_EPI) { if (wr == 0) PG8_BAR; }
;         E(acc, cur, wr, wc, fr, fq);
;         if (!has_next) break;
;         bool keep = false;
;         if constexpr (Epi::CAN_KEEP) keep = (cur.kind < 2);
;         if (!keep) {
; #pragma unroll
;         for (int a = 0; a < 2; ++a)
; #pragma unroll
;             for (int b = 0; b < 2; ++b)
; #pragma unroll
;                 for (int m = 0; m < 4; ++m)
; #pragma unroll
;                     for (int n = 0; n < 2; ++n) acc[a][b][m][n] = (f32x4){0.f, 0.f, 0.f, 0.f};
;         }
;         cur = nxt; cA = nA; cB = nB; ++ui;
;         if constexpr (ALIGN_EPI) { if (wr == 1) PG8_BAR; }
;     __device__ __forceinline__ void operator()(const f32x4 (&acc)[2][2][4][2], const Unit& u, int wr, int wc, int fr, int fq) const {
;     ...
;                 for (int mm = 0; mm < 2; ++mm) {
;                     const int r = row0 + ai * HALF + (2 * m2 + mm) * 16;
;                     float ps = 0.f, pq = 0.f;
; #pragma unroll
;                     for (int bj = 0; bj < 2; ++bj)
; #pragma unroll
;                         for (int n = 0; n < 2; ++n) {
;                             const f32x4 x = (xv[mm][bj][n] - st[mm][0]) * (gg[bj][n] * st[mm][1]) + bb[bj][n];
;                             const f32x4 o = x * alpha + acc[ai][bj][2 * m2 + mm][n] * scale;
;                             const size_t off = (size_t)r * D + col0 + bj * HALF + n * 16;
;                             *(f32x4*)(Y + off) = o;
	v_sub_f32_e32 v25, v45, v66
	v_sub_f32_e32 v24, v44, v66
	v_sub_f32_e32 v27, v47, v66
	v_sub_f32_e32 v26, v46, v66
	v_pk_fma_f32 v[26:27], v[26:27], v[30:31], v[106:107]
	v_pk_fma_f32 v[24:25], v[24:25], v[28:29], v[104:105]
	v_pk_mul_f32 v[26:27], v[26:27], s[16:17] op_sel_hi:[1,0]
	v_pk_mul_f32 v[24:25], v[24:25], s[16:17] op_sel_hi:[1,0]
	v_pk_fma_f32 v[22:23], v[22:23], 0.5, v[26:27] op_sel_hi:[1,0,1]
	v_pk_fma_f32 v[20:21], v[20:21], 0.5, v[24:25] op_sel_hi:[1,0,1]
	ds_bpermute_b32 v246, v238, v20
	ds_bpermute_b32 v247, v238, v21
	ds_bpermute_b32 v248, v238, v22
	ds_bpermute_b32 v249, v238, v23
	v_lshl_add_u64 v[244:245], v[32:33], 0, v[240:241]
	s_waitcnt lgkmcnt(0)
	global_store_dwordx4 v[244:245], v[246:249], off offset:512
	v_pk_mul_f32 v[24:25], v[100:101], v[72:73] op_sel_hi:[1,0]
	v_pk_mul_f32 v[26:27], v[102:103], v[72:73] op_sel_hi:[1,0]
	v_sub_f32_e32 v21, v41, v66
	v_sub_f32_e32 v20, v40, v66
	v_sub_f32_e32 v23, v43, v66
	v_sub_f32_e32 v22, v42, v66
	v_pk_fma_f32 v[22:23], v[22:23], v[26:27], v[98:99]
	v_pk_fma_f32 v[20:21], v[20:21], v[24:25], v[96:97]
	v_pk_mul_f32 v[22:23], v[22:23], s[16:17] op_sel_hi:[1,0]
	v_pk_mul_f32 v[20:21], v[20:21], s[16:17] op_sel_hi:[1,0]
	v_pk_fma_f32 v[14:15], v[14:15], 0.5, v[22:23] op_sel_hi:[1,0,1]
	v_pk_fma_f32 v[12:13], v[12:13], 0.5, v[20:21] op_sel_hi:[1,0,1]
	ds_bpermute_b32 v250, v238, v12
	ds_bpermute_b32 v251, v238, v13
	ds_bpermute_b32 v252, v238, v14
	ds_bpermute_b32 v253, v238, v15
	v_lshl_add_u64 v[244:245], v[32:33], 0, v[240:241]
	s_waitcnt lgkmcnt(0)
	global_store_dwordx4 v[244:245], v[250:253], off offset:576
	v_pk_mul_f32 v[20:21], v[124:125], v[74:75] op_sel_hi:[1,0]
	v_pk_mul_f32 v[22:23], v[126:127], v[74:75] op_sel_hi:[1,0]
	s_waitcnt vmcnt(7)
	v_sub_f32_e32 v13, v49, v68
	v_sub_f32_e32 v12, v48, v68
	v_sub_f32_e32 v15, v51, v68
	v_sub_f32_e32 v14, v50, v68
	v_pk_fma_f32 v[12:13], v[12:13], v[20:21], v[120:121]
	v_pk_fma_f32 v[14:15], v[14:15], v[22:23], v[122:123]
	v_pk_mul_f32 v[12:13], v[12:13], s[16:17] op_sel_hi:[1,0]
	v_pk_mul_f32 v[14:15], v[14:15], s[16:17] op_sel_hi:[1,0]
	v_pk_fma_f32 v[12:13], v[16:17], 0.5, v[12:13] op_sel_hi:[1,0,1]
	v_lshl_add_u64 v[16:17], s[38:39], 0, v[70:71]
	v_pk_fma_f32 v[14:15], v[18:19], 0.5, v[14:15] op_sel_hi:[1,0,1]
	v_lshl_add_u64 v[16:17], v[16:17], 0, v[168:169]
	ds_bpermute_b32 v246, v238, v12
	ds_bpermute_b32 v247, v238, v13
	ds_bpermute_b32 v248, v238, v14
	ds_bpermute_b32 v249, v238, v15
	v_lshl_add_u64 v[244:245], v[16:17], 0, v[240:241]
	s_waitcnt lgkmcnt(0)
	global_store_dwordx4 v[244:245], v[246:249], off
	v_pk_mul_f32 v[18:19], v[116:117], v[74:75] op_sel_hi:[1,0]
	v_pk_mul_f32 v[20:21], v[118:119], v[74:75] op_sel_hi:[1,0]
	s_waitcnt vmcnt(7)
	v_sub_f32_e32 v13, v53, v68
	v_sub_f32_e32 v12, v52, v68
	v_sub_f32_e32 v15, v55, v68
	v_sub_f32_e32 v14, v54, v68
	v_pk_fma_f32 v[14:15], v[14:15], v[20:21], v[114:115]
	v_pk_fma_f32 v[12:13], v[12:13], v[18:19], v[112:113]
	v_pk_mul_f32 v[14:15], v[14:15], s[16:17] op_sel_hi:[1,0]
	v_pk_mul_f32 v[12:13], v[12:13], s[16:17] op_sel_hi:[1,0]
	v_pk_fma_f32 v[10:11], v[10:11], 0.5, v[14:15] op_sel_hi:[1,0,1]
	v_pk_fma_f32 v[8:9], v[8:9], 0.5, v[12:13] op_sel_hi:[1,0,1]
	ds_bpermute_b32 v250, v238, v8
	ds_bpermute_b32 v251, v238, v9
	ds_bpermute_b32 v252, v238, v10
	ds_bpermute_b32 v253, v238, v11
	v_lshl_add_u64 v[244:245], v[16:17], 0, v[240:241]
	s_waitcnt lgkmcnt(0)
	global_store_dwordx4 v[244:245], v[250:253], off offset:64
	v_pk_mul_f32 v[12:13], v[108:109], v[74:75] op_sel_hi:[1,0]
	v_pk_mul_f32 v[14:15], v[110:111], v[74:75] op_sel_hi:[1,0]
	s_waitcnt vmcnt(7)
	v_sub_f32_e32 v9, v57, v68
	v_sub_f32_e32 v8, v56, v68
	v_sub_f32_e32 v11, v59, v68
	v_sub_f32_e32 v10, v58, v68
	v_pk_fma_f32 v[10:11], v[10:11], v[14:15], v[106:107]
	v_pk_fma_f32 v[8:9], v[8:9], v[12:13], v[104:105]
	v_pk_mul_f32 v[10:11], v[10:11], s[16:17] op_sel_hi:[1,0]
	v_pk_mul_f32 v[8:9], v[8:9], s[16:17] op_sel_hi:[1,0]
	v_pk_fma_f32 v[6:7], v[6:7], 0.5, v[10:11] op_sel_hi:[1,0,1]
	v_pk_fma_f32 v[4:5], v[4:5], 0.5, v[8:9] op_sel_hi:[1,0,1]
	ds_bpermute_b32 v246, v238, v4
	ds_bpermute_b32 v247, v238, v5
	ds_bpermute_b32 v248, v238, v6
	ds_bpermute_b32 v249, v238, v7
	v_lshl_add_u64 v[244:245], v[16:17], 0, v[240:241]
	s_waitcnt lgkmcnt(0)
	global_store_dwordx4 v[244:245], v[246:249], off offset:512
	v_pk_mul_f32 v[8:9], v[100:101], v[74:75] op_sel_hi:[1,0]
	v_pk_mul_f32 v[10:11], v[102:103], v[74:75] op_sel_hi:[1,0]
	s_waitcnt vmcnt(7)
	v_sub_f32_e32 v5, v61, v68
	v_sub_f32_e32 v4, v60, v68
	v_sub_f32_e32 v7, v63, v68
	v_sub_f32_e32 v6, v62, v68
	v_pk_fma_f32 v[6:7], v[6:7], v[10:11], v[98:99]
	v_pk_fma_f32 v[4:5], v[4:5], v[8:9], v[96:97]
	v_pk_mul_f32 v[6:7], v[6:7], s[16:17] op_sel_hi:[1,0]
	v_pk_mul_f32 v[4:5], v[4:5], s[16:17] op_sel_hi:[1,0]
	v_pk_fma_f32 v[2:3], v[2:3], 0.5, v[6:7] op_sel_hi:[1,0,1]
	v_pk_fma_f32 v[0:1], v[0:1], 0.5, v[4:5] op_sel_hi:[1,0,1]
	ds_bpermute_b32 v250, v238, v0
	ds_bpermute_b32 v251, v238, v1
	ds_bpermute_b32 v252, v238, v2
	ds_bpermute_b32 v253, v238, v3
	v_lshl_add_u64 v[244:245], v[16:17], 0, v[240:241]
	s_waitcnt lgkmcnt(0)
	global_store_dwordx4 v[244:245], v[250:253], off offset:576
	s_cbranch_vccnz .LBB0_1112
	s_andn2_b64 vcc, exec, s[6:7]
	s_cbranch_vccnz .LBB0_1111
	s_barrier
	s_branch .LBB0_1111

; __device__ __forceinline__ void ln_row(const float* yrow, const float* g, const float* b, float* of, bf16_t* ob, int lane) {
;     f32x4 v[8]; float s = 0.f;
; #pragma unroll
;     for (int j = 0; j < 8; ++j) { v[j] = *(const f32x4*)(yrow + 4 * lane + 256 * j); s += (v[j][0] + v[j][1]) + (v[j][2] + v[j][3]); }
;     const float mean = wave_sum(s) * (1.f / D); float s2 = 0.f;
; #pragma unroll
;     for (int j = 0; j < 8; ++j) { v[j] = v[j] - mean; s2 += (v[j][0] * v[j][0] + v[j][1] * v[j][1]) + (v[j][2] * v[j][2] + v[j][3] * v[j][3]); }
;     const float rstd = 1.0f / sqrtf(wave_sum(s2) * (1.f / D) + LN_EPS);
; __global__ void __launch_bounds__(NTHREADS, 2) fwd_kernel(Params P) {
;     ...
;     if (PHON(16)) for (int r = gw; r < MR; r += NGW) ln_row(Y + (size_t)r * D, P.in[I_LN3G], P.in[I_LN3B], out + O_Y + (size_t)r * D, nullptr, lane);
.LBB0_1182:
	v_lshl_add_u64 v[16:17], s[4:5], 0, v[176:177]
	v_add_co_u32_e32 v18, vcc, s10, v16
	s_nop 1
	v_addc_co_u32_e32 v19, vcc, 0, v17, vcc
	v_add_co_u32_e32 v60, vcc, 0x1a320000, v16
	global_load_dwordx4 v[8:11], v[18:19], off nt
	global_load_dwordx4 v[12:15], v[18:19], off offset:1024 nt
	global_load_dwordx4 v[4:7], v[18:19], off offset:2048 nt
	global_load_dwordx4 v[0:3], v[18:19], off offset:3072 nt
	s_waitcnt lgkmcnt(0)
	v_addc_co_u32_e32 v61, vcc, 0, v17, vcc
	global_load_dwordx4 v[28:31], v[60:61], off nt
	global_load_dwordx4 v[24:27], v[60:61], off offset:1024 nt
	global_load_dwordx4 v[20:23], v[60:61], off offset:2048 nt
	global_load_dwordx4 v[16:19], v[60:61], off offset:3072 nt
	s_and_b64 vcc, exec, s[0:1]
	s_waitcnt vmcnt(7)
	v_mov_b32_e32 v63, v10
	s_waitcnt vmcnt(6)
	v_mov_b32_e32 v66, v13
	v_mov_b32_e32 v67, v14
	v_mov_b32_e32 v68, v12
	v_mov_b32_e32 v69, v15
	s_waitcnt vmcnt(5)
	v_add_f32_e32 v70, v4, v5
	v_add_f32_e32 v72, v6, v7
	s_waitcnt vmcnt(4)
	v_mov_b32_e32 v71, v2
	v_mov_b32_e32 v73, v3
	s_waitcnt vmcnt(3)
	v_mov_b32_e32 v74, v28
	s_waitcnt vmcnt(2)
	v_mov_b32_e32 v75, v24
	v_mov_b32_e32 v76, v29
	v_mov_b32_e32 v77, v25
	v_mov_b32_e32 v78, v30
	v_mov_b32_e32 v79, v26
	v_mov_b32_e32 v80, v31
	v_mov_b32_e32 v81, v27
	v_mov_b32_e32 v65, v11
	s_waitcnt vmcnt(1)
	v_mov_b32_e32 v82, v21
	v_mov_b32_e32 v83, v22
	v_mov_b32_e32 v84, v20
	v_mov_b32_e32 v85, v23
	s_waitcnt vmcnt(0)
	v_add_f32_e32 v62, v16, v17
	v_add_f32_e32 v64, v18, v19
	v_pk_add_f32 v[66:67], v[66:67], v[68:69]
	v_pk_add_f32 v[68:69], v[70:71], v[72:73]
	v_pk_add_f32 v[70:71], v[74:75], v[76:77]
	v_pk_add_f32 v[72:73], v[78:79], v[80:81]
	v_pk_add_f32 v[74:75], v[82:83], v[84:85]
	v_pk_add_f32 v[62:63], v[62:63], v[64:65]
	v_pk_add_f32 v[64:65], v[66:67], v[66:67] op_sel:[0,1] op_sel_hi:[1,0]
	v_pk_add_f32 v[66:67], v[70:71], v[72:73]
	v_pk_add_f32 v[70:71], v[74:75], v[74:75] op_sel:[0,1] op_sel_hi:[1,0]
	v_add_f32_e32 v60, 0, v66
	v_mov_b32_e32 v61, v8
	v_mov_b32_e32 v71, v9
	v_add_f32_e32 v60, v60, v67
	v_pk_add_f32 v[60:61], v[60:61], v[70:71]
	v_mov_b32_e32 v65, v1
	v_pk_add_f32 v[60:61], v[60:61], v[62:63]
	s_nop 0
	v_pk_add_f32 v[60:61], v[60:61], v[60:61] op_sel:[0,1] op_sel_hi:[1,0]
	s_nop 0
	v_mov_b32_e32 v61, v0
	v_pk_add_f32 v[60:61], v[60:61], v[64:65]
	s_nop 0
	v_pk_add_f32 v[60:61], v[60:61], v[68:69]
	s_nop 0
	v_add_f32_e32 v60, v60, v61
	ds_bpermute_b32 v61, v52, v60
	s_waitcnt lgkmcnt(0)
	v_add_f32_e32 v60, v60, v61
	ds_bpermute_b32 v61, v53, v60
	s_waitcnt lgkmcnt(0)
	v_add_f32_e32 v60, v60, v61
	ds_bpermute_b32 v61, v54, v60
	s_waitcnt lgkmcnt(0)
	v_add_f32_e32 v60, v60, v61
	ds_bpermute_b32 v61, v55, v60
	s_waitcnt lgkmcnt(0)
	v_add_f32_e32 v60, v60, v61
	ds_bpermute_b32 v61, v56, v60
	s_waitcnt lgkmcnt(0)
	v_add_f32_e32 v60, v60, v61
	ds_bpermute_b32 v61, v57, v60
	s_waitcnt lgkmcnt(0)
	v_add_f32_e32 v60, v60, v61
	v_fmamk_f32 v31, v60, 0xba000000, v31
	v_fmamk_f32 v29, v60, 0xba000000, v29
	v_fmamk_f32 v27, v60, 0xba000000, v27
	v_fmamk_f32 v25, v60, 0xba000000, v25
	v_fmamk_f32 v30, v60, 0xba000000, v30
	v_fmac_f32_e32 v28, 0xba000000, v60
	v_fmamk_f32 v26, v60, 0xba000000, v26
	v_fmac_f32_e32 v24, 0xba000000, v60
	v_fmamk_f32 v23, v60, 0xba000000, v23
	v_fmamk_f32 v21, v60, 0xba000000, v21
	v_mul_f32_e32 v61, v29, v29
	v_mul_f32_e32 v62, v31, v31
	v_mul_f32_e32 v63, v25, v25
	v_mul_f32_e32 v64, v27, v27
	v_fmamk_f32 v22, v60, 0xba000000, v22
	v_fmac_f32_e32 v20, 0xba000000, v60
	v_fmamk_f32 v19, v60, 0xba000000, v19
	v_fmamk_f32 v17, v60, 0xba000000, v17
	v_mul_f32_e32 v65, v21, v21
	v_mul_f32_e32 v66, v23, v23
	v_fmac_f32_e32 v61, v28, v28
	v_fmac_f32_e32 v62, v30, v30
	v_fmac_f32_e32 v63, v24, v24
	v_fmac_f32_e32 v64, v26, v26
	v_fmamk_f32 v18, v60, 0xba000000, v18
	v_fmac_f32_e32 v16, 0xba000000, v60
	v_fmamk_f32 v11, v60, 0xba000000, v11
	v_fmamk_f32 v9, v60, 0xba000000, v9
	v_mul_f32_e32 v67, v17, v17
	v_mul_f32_e32 v68, v19, v19
	v_fmac_f32_e32 v65, v20, v20
	v_fmac_f32_e32 v66, v22, v22
	v_add_f32_e32 v61, v61, v62
	v_add_f32_e32 v62, v63, v64
	v_fmamk_f32 v10, v60, 0xba000000, v10
	v_fmac_f32_e32 v8, 0xba000000, v60
	v_fmamk_f32 v15, v60, 0xba000000, v15
	v_fmamk_f32 v13, v60, 0xba000000, v13
	v_mul_f32_e32 v69, v9, v9
	v_mul_f32_e32 v70, v11, v11
	v_fmac_f32_e32 v67, v16, v16
	v_fmac_f32_e32 v68, v18, v18
	v_add_f32_e32 v63, v65, v66
	v_add_f32_e32 v61, v61, v62
	v_fmamk_f32 v14, v60, 0xba000000, v14
	v_fmac_f32_e32 v12, 0xba000000, v60
	v_fmamk_f32 v7, v60, 0xba000000, v7
	v_fmamk_f32 v5, v60, 0xba000000, v5
	v_mul_f32_e32 v71, v13, v13
	v_mul_f32_e32 v72, v15, v15
	v_fmac_f32_e32 v69, v8, v8
	v_fmac_f32_e32 v70, v10, v10
	v_add_f32_e32 v64, v67, v68
	v_add_f32_e32 v61, v63, v61
	v_fmamk_f32 v6, v60, 0xba000000, v6
	v_fmac_f32_e32 v4, 0xba000000, v60
	v_mul_f32_e32 v73, v5, v5
	v_fmac_f32_e32 v71, v12, v12
	v_fmac_f32_e32 v72, v14, v14
	v_add_f32_e32 v65, v69, v70
	v_add_f32_e32 v61, v64, v61
	v_mul_f32_e32 v62, v7, v7
	v_fmac_f32_e32 v73, v4, v4
	v_add_f32_e32 v66, v71, v72
	v_add_f32_e32 v61, v65, v61
	v_fmac_f32_e32 v62, v6, v6
	v_add_f32_e32 v61, v66, v61
	v_add_f32_e32 v62, v73, v62
	v_fmamk_f32 v3, v60, 0xba000000, v3
	v_fmamk_f32 v1, v60, 0xba000000, v1
	v_add_f32_e32 v61, v62, v61
	v_fmamk_f32 v2, v60, 0xba000000, v2
	v_fmac_f32_e32 v0, 0xba000000, v60
	v_mul_f32_e32 v60, v1, v1
	v_mul_f32_e32 v62, v3, v3
	v_fmac_f32_e32 v60, v0, v0
	v_fmac_f32_e32 v62, v2, v2
	v_add_f32_e32 v60, v60, v62
	v_add_f32_e32 v60, v60, v61
	ds_bpermute_b32 v61, v52, v60
	s_waitcnt lgkmcnt(0)
	v_add_f32_e32 v60, v60, v61
	ds_bpermute_b32 v61, v53, v60
	s_waitcnt lgkmcnt(0)
	v_add_f32_e32 v60, v60, v61
	ds_bpermute_b32 v61, v54, v60
	s_waitcnt lgkmcnt(0)
	v_add_f32_e32 v60, v60, v61
	ds_bpermute_b32 v61, v55, v60
	s_waitcnt lgkmcnt(0)
	v_add_f32_e32 v60, v60, v61
	ds_bpermute_b32 v61, v56, v60
	s_waitcnt lgkmcnt(0)
	v_add_f32_e32 v60, v60, v61
	ds_bpermute_b32 v61, v57, v60
	s_cbranch_vccnz .LBB0_1181
; __device__ __forceinline__ unsigned cvt_pk_bf16(float lo, float hi) { unsigned r; asm volatile("v_cvt_pk_bf16_f32 %0, %1, %2" : "=v"(r) : "v"(lo), "v"(hi)); return r; }
; __device__ __forceinline__ void ln_row(const float* yrow, const float* g, const float* b, float* of, bf16_t* ob, int lane) {
;     ...
;     const float rstd = 1.0f / sqrtf(wave_sum(s2) * (1.f / D) + LN_EPS);
; #pragma unroll
;     for (int j = 0; j < 8; ++j) {
;         const f32x4 gg = *(const f32x4*)(g + 4 * lane + 256 * j), bb = *(const f32x4*)(b + 4 * lane + 256 * j);
;         const f32x4 o = v[j] * rstd * gg + bb;
;         if (of) __builtin_nontemporal_store(o, (f32x4*)(of + 4 * lane + 256 * j));
;         if (ob) { u32x2 w; w.x = cvt_pk_bf16(o[0], o[1]); w.y = cvt_pk_bf16(o[2], o[3]); *(u32x2*)(ob + 4 * lane + 256 * j) = w; }
;     }
	v_mov_b32_e32 v62, v100
	v_mov_b32_e32 v63, v101
	v_mov_b32_e32 v64, v102
	v_mov_b32_e32 v65, v103
	v_mov_b32_e32 v66, v104
	v_mov_b32_e32 v67, v105
	v_mov_b32_e32 v68, v106
	v_mov_b32_e32 v69, v107
	s_waitcnt lgkmcnt(0)
	v_add_f32_e32 v60, v60, v61
	v_fmamk_f32 v60, v60, 0x3a000000, v58
	v_mul_f32_e32 v61, 0x4f800000, v60
	v_cmp_gt_f32_e32 vcc, s11, v60
	s_nop 1
	v_cndmask_b32_e32 v60, v60, v61, vcc
	v_sqrt_f32_e32 v61, v60
	s_nop 0
	v_add_u32_e32 v70, -1, v61
	v_add_u32_e32 v71, 1, v61
	v_fma_f32 v72, -v70, v61, v60
	v_fma_f32 v73, -v71, v61, v60
	v_cmp_ge_f32_e64 s[2:3], 0, v72
	s_nop 1
	v_cndmask_b32_e64 v61, v61, v70, s[2:3]
	v_cmp_lt_f32_e64 s[2:3], 0, v73
	s_nop 1
	v_cndmask_b32_e64 v61, v61, v71, s[2:3]
	v_mul_f32_e32 v70, 0x37800000, v61
	v_cndmask_b32_e32 v61, v61, v70, vcc
	v_cmp_class_f32_e32 vcc, v60, v59
	v_lshl_add_u64 v[70:71], s[8:9], 0, v[176:177]
	s_nop 0
	v_cndmask_b32_e32 v60, v61, v60, vcc
	v_div_scale_f32 v61, s[2:3], v60, v60, 1.0
	v_rcp_f32_e32 v72, v61
	v_div_scale_f32 v73, vcc, 1.0, v60, 1.0
	v_fma_f32 v74, -v61, v72, 1.0
	v_fmac_f32_e32 v72, v74, v72
	v_mul_f32_e32 v74, v73, v72
	v_fma_f32 v75, -v61, v74, v73
	v_fmac_f32_e32 v74, v75, v72
	v_fma_f32 v61, -v61, v74, v73
	v_div_fmas_f32 v61, v61, v72, v74
	v_div_fixup_f32 v72, v61, v60, 1.0
	v_pk_mul_f32 v[28:29], v[28:29], v[72:73] op_sel_hi:[1,0]
	v_pk_mul_f32 v[30:31], v[30:31], v[72:73] op_sel_hi:[1,0]
	v_pk_mul_f32 v[26:27], v[26:27], v[72:73] op_sel_hi:[1,0]
	v_pk_mul_f32 v[24:25], v[24:25], v[72:73] op_sel_hi:[1,0]
	v_pk_mul_f32 v[22:23], v[22:23], v[72:73] op_sel_hi:[1,0]
	v_pk_mul_f32 v[20:21], v[20:21], v[72:73] op_sel_hi:[1,0]
	v_pk_mul_f32 v[18:19], v[18:19], v[72:73] op_sel_hi:[1,0]
	v_pk_mul_f32 v[16:17], v[16:17], v[72:73] op_sel_hi:[1,0]
	v_pk_mul_f32 v[10:11], v[10:11], v[72:73] op_sel_hi:[1,0]
	v_pk_mul_f32 v[8:9], v[8:9], v[72:73] op_sel_hi:[1,0]
	v_pk_mul_f32 v[14:15], v[14:15], v[72:73] op_sel_hi:[1,0]
	v_pk_mul_f32 v[12:13], v[12:13], v[72:73] op_sel_hi:[1,0]
	v_pk_mul_f32 v[6:7], v[6:7], v[72:73] op_sel_hi:[1,0]
	v_pk_mul_f32 v[4:5], v[4:5], v[72:73] op_sel_hi:[1,0]
	v_pk_mul_f32 v[2:3], v[2:3], v[72:73] op_sel_hi:[1,0]
	v_pk_mul_f32 v[0:1], v[0:1], v[72:73] op_sel_hi:[1,0]
	s_nop 0
	v_pk_fma_f32 v[30:31], v[30:31], v[64:65], v[68:69]
	v_pk_fma_f32 v[28:29], v[28:29], v[62:63], v[66:67]
	global_store_dwordx4 v[70:71], v[28:31], off nt
	s_nop 1
	v_mov_b32_e32 v28, v108
	v_mov_b32_e32 v29, v109
	v_mov_b32_e32 v30, v110
	v_mov_b32_e32 v31, v111
	v_mov_b32_e32 v60, v112
	v_mov_b32_e32 v61, v113
	v_mov_b32_e32 v62, v114
	v_mov_b32_e32 v63, v115
	s_nop 0
	v_pk_fma_f32 v[24:25], v[24:25], v[28:29], v[60:61]
	v_pk_fma_f32 v[26:27], v[26:27], v[30:31], v[62:63]
	global_store_dwordx4 v[70:71], v[24:27], off offset:1024 nt
	s_nop 1
	v_mov_b32_e32 v24, v116
	v_mov_b32_e32 v25, v117
	v_mov_b32_e32 v26, v118
	v_mov_b32_e32 v27, v119
	v_mov_b32_e32 v28, v120
	v_mov_b32_e32 v29, v121
	v_mov_b32_e32 v30, v122
	v_mov_b32_e32 v31, v123
	s_nop 0
	v_pk_fma_f32 v[20:21], v[20:21], v[24:25], v[28:29]
	v_pk_fma_f32 v[22:23], v[22:23], v[26:27], v[30:31]
	global_store_dwordx4 v[70:71], v[20:23], off offset:2048 nt
	s_nop 1
	v_mov_b32_e32 v20, v124
	v_mov_b32_e32 v21, v125
	v_mov_b32_e32 v22, v126
	v_mov_b32_e32 v23, v127
	v_mov_b32_e32 v24, v128
	v_mov_b32_e32 v25, v129
	v_mov_b32_e32 v26, v130
	v_mov_b32_e32 v27, v131
	s_nop 0
	v_pk_fma_f32 v[16:17], v[16:17], v[20:21], v[24:25]
	v_pk_fma_f32 v[18:19], v[18:19], v[22:23], v[26:27]
	global_store_dwordx4 v[70:71], v[16:19], off offset:3072 nt
	s_nop 1
	v_mov_b32_e32 v16, v132
	v_mov_b32_e32 v17, v133
	v_mov_b32_e32 v18, v134
	v_mov_b32_e32 v19, v135
	v_mov_b32_e32 v20, v136
	v_mov_b32_e32 v21, v137
	v_mov_b32_e32 v22, v138
	v_mov_b32_e32 v23, v139
	v_add_co_u32_e32 v24, vcc, s12, v70
	s_nop 0
	v_pk_fma_f32 v[8:9], v[8:9], v[16:17], v[20:21]
	v_addc_co_u32_e32 v25, vcc, 0, v71, vcc
	v_pk_fma_f32 v[10:11], v[10:11], v[18:19], v[22:23]
	global_store_dwordx4 v[24:25], v[8:11], off nt
	s_nop 1
	v_mov_b32_e32 v8, v140
	v_mov_b32_e32 v9, v141
	v_mov_b32_e32 v10, v142
	v_mov_b32_e32 v11, v143
	v_mov_b32_e32 v16, v144
	v_mov_b32_e32 v17, v145
	v_mov_b32_e32 v18, v146
	v_mov_b32_e32 v19, v147
	s_nop 0
	v_pk_fma_f32 v[8:9], v[12:13], v[8:9], v[16:17]
	v_pk_fma_f32 v[10:11], v[14:15], v[10:11], v[18:19]
	global_store_dwordx4 v[24:25], v[8:11], off offset:1024 nt
	s_nop 1
	v_mov_b32_e32 v8, v148
	v_mov_b32_e32 v9, v149
	v_mov_b32_e32 v10, v150
	v_mov_b32_e32 v11, v151
	v_mov_b32_e32 v12, v152
	v_mov_b32_e32 v13, v153
	v_mov_b32_e32 v14, v154
	v_mov_b32_e32 v15, v155
	s_nop 0
	v_pk_fma_f32 v[4:5], v[4:5], v[8:9], v[12:13]
	v_pk_fma_f32 v[6:7], v[6:7], v[10:11], v[14:15]
	global_store_dwordx4 v[24:25], v[4:7], off offset:2048 nt
	s_nop 1
	v_mov_b32_e32 v4, v156
	v_mov_b32_e32 v5, v157
	v_mov_b32_e32 v6, v158
	v_mov_b32_e32 v7, v159
	v_mov_b32_e32 v8, v160
	v_mov_b32_e32 v9, v161
	v_mov_b32_e32 v10, v162
	v_mov_b32_e32 v11, v163
	s_nop 0
	v_pk_fma_f32 v[0:1], v[0:1], v[4:5], v[8:9]
	v_pk_fma_f32 v[2:3], v[2:3], v[6:7], v[10:11]
	global_store_dwordx4 v[24:25], v[0:3], off offset:3072 nt
	s_nop 1
	s_branch .LBB0_1181
